# v039 + P7 row pass unrolled with next-row prefetch
# baseline (speedup 1.0000x reference)
; __device__ __forceinline__ void rows_norm_mod(Ctx& X, const float* src, const bf16_t* delta, float* x1out, const float* w, const float* sc, const float* sh, bf16_t* dst, bool do_cs) {
;     f32x4 pa[8], pb[8];
; #pragma unroll
;     for (int j = 0; j < 8; ++j) { const int col = 4 * X.lane + 256 * j; pa[j] = *(const f32x4*)(w + col) * (*(const f32x4*)(sc + col) + 1.f); pb[j] = *(const f32x4*)(sh + col); }
;     for (int row = X.gw; row < S; row += X.NGW) {
;         const f32x4* xr = (const f32x4*)(src + (size_t)row * D) + X.lane;
.LBB0_864:
	s_cmp_lt_i32 s92, 8
	s_cselect_b64 s[2:3], -1, 0
	s_and_b64 s[0:1], s[2:3], s[0:1]
	s_andn2_b64 vcc, exec, s[0:1]
	s_cbranch_vccnz .LBB0_868
	s_cmpk_gt_i32 s48, 0x3fff
	s_cbranch_scc1 .LBB0_868
	s_add_u32 s4, s90, 0x8000
	s_addc_u32 s5, s91, 0
	v_lshlrev_b32_e32 v32, 4, v208
	global_load_dwordx4 v[34:37], v32, s[4:5]
	v_readlane_b32 s8, v245, 5
	v_or_b32_e32 v33, 0x400, v32
	v_or_b32_e32 v98, 0x800, v32
	v_or_b32_e32 v99, 0xc00, v32
	v_or_b32_e32 v100, 0x1000, v32
	v_or_b32_e32 v101, 0x1400, v32
	v_or_b32_e32 v102, 0x1800, v32
	v_or_b32_e32 v103, 0x1c00, v32
	v_readlane_b32 s12, v245, 9
	v_readlane_b32 s13, v245, 10
	global_load_dwordx4 v[38:41], v33, s[4:5]
	global_load_dwordx4 v[42:45], v98, s[4:5]
	global_load_dwordx4 v[46:49], v99, s[4:5]
	global_load_dwordx4 v[50:53], v100, s[4:5]
	global_load_dwordx4 v[54:57], v101, s[4:5]
	global_load_dwordx4 v[58:61], v102, s[4:5]
	global_load_dwordx4 v[62:65], v103, s[4:5]
	global_load_dwordx4 v[66:69], v32, s[12:13]
	global_load_dwordx4 v[70:73], v32, s[12:13] offset:1024
	global_load_dwordx4 v[74:77], v32, s[12:13] offset:2048
	global_load_dwordx4 v[78:81], v32, s[12:13] offset:3072
	global_load_dwordx4 v[82:85], v100, s[12:13]
	global_load_dwordx4 v[86:89], v101, s[12:13]
	global_load_dwordx4 v[90:93], v102, s[12:13]
	global_load_dwordx4 v[94:97], v103, s[12:13]
	s_add_u32 s2, s90, 0x6000
	v_mbcnt_lo_u32_b32 v0, -1, 0
	s_addc_u32 s3, s91, 0
	v_mbcnt_hi_u32_b32 v104, -1, v0
	global_load_dwordx4 v[0:3], v32, s[2:3]
	global_load_dwordx4 v[4:7], v33, s[2:3]
	global_load_dwordx4 v[8:11], v98, s[2:3]
	global_load_dwordx4 v[12:15], v99, s[2:3]
	global_load_dwordx4 v[16:19], v100, s[2:3]
	global_load_dwordx4 v[20:23], v101, s[2:3]
	global_load_dwordx4 v[24:27], v102, s[2:3]
	global_load_dwordx4 v[28:31], v103, s[2:3]
	v_and_b32_e32 v105, 64, v104
	v_xor_b32_e32 v106, 1, v104
	v_add_u32_e32 v33, 64, v105
	v_xor_b32_e32 v107, 2, v104
	v_cmp_lt_i32_e32 vcc, v106, v33
	v_xor_b32_e32 v108, 4, v104
	s_ashr_i32 s49, s48, 31
	v_cndmask_b32_e32 v98, v104, v106, vcc
	v_cmp_lt_i32_e32 vcc, v107, v33
	s_lshl_b64 s[2:3], s[48:49], 13
	s_add_u32 s2, s52, s2
	v_cndmask_b32_e32 v99, v104, v107, vcc
	v_cmp_lt_i32_e32 vcc, v108, v33
	s_addc_u32 s3, s53, s3
	v_lshlrev_b32_e32 v120, 2, v98
	v_cndmask_b32_e32 v100, v104, v108, vcc
	v_lshlrev_b32_e32 v121, 2, v99
	s_ashr_i32 s51, s50, 31
	s_lshl_b64 s[4:5], s[50:51], 13
	v_readlane_b32 s9, v245, 6
	s_mov_b64 s[8:9], s[12:13]
	v_lshlrev_b32_e32 v122, 2, v100
	v_mov_b32_e32 v126, 0x358637bd
	s_mov_b32 s8, 0xed001000
	s_mov_b32 s9, s48
	v_readlane_b32 s10, v245, 7
	v_readlane_b32 s11, v245, 8
	v_readlane_b32 s14, v245, 11
	v_readlane_b32 s15, v245, 12
	v_readlane_b32 s16, v245, 13
	v_readlane_b32 s17, v245, 14
	v_readlane_b32 s18, v245, 15
	v_readlane_b32 s19, v245, 16
	v_readlane_b32 s20, v245, 17
	v_readlane_b32 s21, v245, 18
	v_readlane_b32 s22, v245, 19
	v_readlane_b32 s23, v245, 20
	s_waitcnt vmcnt(23)
	v_pk_add_f32 v[34:35], v[34:35], 1.0 op_sel_hi:[1,0]
	v_pk_add_f32 v[36:37], v[36:37], 1.0 op_sel_hi:[1,0]
	s_waitcnt vmcnt(15)
	v_pk_mul_f32 v[66:67], v[66:67], v[34:35]
	v_xor_b32_e32 v34, 8, v104
	v_cmp_lt_i32_e32 vcc, v34, v33
	v_pk_add_f32 v[40:41], v[40:41], 1.0 op_sel_hi:[1,0]
	v_pk_add_f32 v[44:45], v[44:45], 1.0 op_sel_hi:[1,0]
	v_cndmask_b32_e32 v34, v104, v34, vcc
	v_lshlrev_b32_e32 v123, 2, v34
	v_xor_b32_e32 v34, 16, v104
	v_cmp_lt_i32_e32 vcc, v34, v33
	v_pk_add_f32 v[48:49], v[48:49], 1.0 op_sel_hi:[1,0]
	v_pk_add_f32 v[52:53], v[52:53], 1.0 op_sel_hi:[1,0]
	v_cndmask_b32_e32 v34, v104, v34, vcc
	v_lshlrev_b32_e32 v124, 2, v34
	v_xor_b32_e32 v34, 32, v104
	v_cmp_lt_i32_e32 vcc, v34, v33
	v_pk_add_f32 v[56:57], v[56:57], 1.0 op_sel_hi:[1,0]
	v_pk_add_f32 v[60:61], v[60:61], 1.0 op_sel_hi:[1,0]
	v_cndmask_b32_e32 v33, v104, v34, vcc
	v_lshlrev_b32_e32 v125, 2, v33
	v_mov_b32_e32 v33, 0
	v_pk_add_f32 v[98:99], v[64:65], 1.0 op_sel_hi:[1,0]
	v_lshl_add_u64 v[34:35], s[2:3], 0, v[32:33]
	s_mov_b64 s[2:3], 0x1000
	v_pk_mul_f32 v[64:65], v[68:69], v[36:37]
	s_waitcnt vmcnt(14)
	v_pk_mul_f32 v[68:69], v[72:73], v[40:41]
	s_waitcnt vmcnt(13)
	v_pk_mul_f32 v[72:73], v[76:77], v[44:45]
	s_waitcnt vmcnt(12)
	v_pk_mul_f32 v[76:77], v[80:81], v[48:49]
	s_waitcnt vmcnt(11)
	v_pk_mul_f32 v[80:81], v[84:85], v[52:53]
	s_waitcnt vmcnt(10)
	v_pk_mul_f32 v[84:85], v[88:89], v[56:57]
	s_waitcnt vmcnt(9)
	v_pk_mul_f32 v[88:89], v[92:93], v[60:61]
	s_waitcnt vmcnt(8)
	v_pk_mul_f32 v[92:93], v[96:97], v[98:99]
	v_lshl_add_u64 v[96:97], v[34:35], 0, s[2:3]
	s_lshl_b64 s[2:3], s[48:49], 12
	s_add_u32 s2, s90, s2
	v_lshlrev_b32_e32 v32, 3, v208
	s_addc_u32 s3, s91, s3
	v_pk_add_f32 v[38:39], v[38:39], 1.0 op_sel_hi:[1,0]
	v_pk_add_f32 v[42:43], v[42:43], 1.0 op_sel_hi:[1,0]
	v_pk_add_f32 v[46:47], v[46:47], 1.0 op_sel_hi:[1,0]
	v_pk_add_f32 v[50:51], v[50:51], 1.0 op_sel_hi:[1,0]
	v_pk_add_f32 v[54:55], v[54:55], 1.0 op_sel_hi:[1,0]
	v_pk_add_f32 v[58:59], v[58:59], 1.0 op_sel_hi:[1,0]
	v_pk_add_f32 v[62:63], v[62:63], 1.0 op_sel_hi:[1,0]
	v_lshl_add_u64 v[32:33], s[2:3], 0, v[32:33]
	s_mov_b64 s[2:3], 0x18300000
	v_pk_mul_f32 v[70:71], v[70:71], v[38:39]
	v_pk_mul_f32 v[74:75], v[74:75], v[42:43]
	v_pk_mul_f32 v[78:79], v[78:79], v[46:47]
	v_pk_mul_f32 v[82:83], v[82:83], v[50:51]
	v_pk_mul_f32 v[86:87], v[86:87], v[54:55]
	v_pk_mul_f32 v[90:91], v[90:91], v[58:59]
	v_pk_mul_f32 v[94:95], v[94:95], v[62:63]
	v_lshl_add_u64 v[98:99], v[32:33], 0, s[2:3]
	s_lshl_b64 s[6:7], s[50:51], 12
	s_mov_b32 s2, 0x800000
	s_mov_b32 s3, 0xed000000
	s_cmp_lg_u32 s94, 0x100
	s_cbranch_scc1 .LBB0_867
; __device__ __forceinline__ float bflo(unsigned w) { return __uint_as_float(w << 16); }
; __device__ __forceinline__ float bfhi(unsigned w) { return __uint_as_float(w & 0xffff0000u); }
; __device__ __forceinline__ void rows_norm_mod(Ctx& X, const float* src, const bf16_t* delta, float* x1out, const float* w, const float* sc, const float* sh, bf16_t* dst, bool do_cs) {
;     ...
;     for (int row = X.gw; row < S; row += X.NGW) {
;         const f32x4* xr = (const f32x4*)(src + (size_t)row * D) + X.lane;
;         f32x4 v[8]; float ss = 0.f;
; #pragma unroll
;         for (int j = 0; j < 8; ++j) v[j] = __builtin_nontemporal_load(xr + 64 * j);
;         if (delta) {
;             const u32x2* dr = (const u32x2*)(delta + (size_t)row * D) + X.lane;
; #pragma unroll
;             for (int j = 0; j < 8; ++j) { const u32x2 d2 = dr[64 * j]; v[j][0] += bflo(d2.x); v[j][1] += bfhi(d2.x); v[j][2] += bflo(d2.y); v[j][3] += bfhi(d2.y); }
;             if (x1out) {
;                 f32x4* xo = (f32x4*)(x1out + (size_t)row * D) + X.lane;
; #pragma unroll
;                 for (int j = 0; j < 8; ++j) xo[64 * j] = v[j];
;             }
;         }
; #pragma unroll
;         for (int j = 0; j < 8; ++j) ss += (v[j][0] * v[j][0] + v[j][1] * v[j][1]) + (v[j][2] * v[j][2] + v[j][3] * v[j][3]);
;         const float r = rsqrtf(wave_sum(ss) * (1.f / D) + EPS);
	s_mov_b32 s24, s48
	s_mov_b32 s25, 0
	s_lshl_b64 s[10:11], s[24:25], 13
	s_add_u32 s10, s10, s52
	s_addc_u32 s11, s11, s53
	s_lshl_b64 s[12:13], s[24:25], 12
	s_add_u32 s12, s12, s90
	s_addc_u32 s13, s13, s91
	s_add_u32 s14, s12, 0x5300000
	s_addc_u32 s15, s13, 0
	s_add_u32 s12, s12, 0x18300000
	s_addc_u32 s13, s13, 0
	v_lshlrev_b32_e32 v186, 4, v208
	v_add_u32_e32 v187, 0x1000, v186
	v_lshlrev_b32_e32 v188, 3, v208
	global_load_dwordx2 v[100:101], v188, s[12:13] offset:0
	global_load_dwordx2 v[102:103], v188, s[12:13] offset:512
	global_load_dwordx2 v[104:105], v188, s[12:13] offset:1024
	global_load_dwordx2 v[106:107], v188, s[12:13] offset:1536
	global_load_dwordx2 v[108:109], v188, s[12:13] offset:2048
	global_load_dwordx2 v[110:111], v188, s[12:13] offset:2560
	global_load_dwordx2 v[112:113], v188, s[12:13] offset:3072
	global_load_dwordx2 v[114:115], v188, s[12:13] offset:3584
	global_load_dwordx4 v[32:35], v186, s[10:11] offset:0 nt
	global_load_dwordx4 v[36:39], v186, s[10:11] offset:1024 nt
	global_load_dwordx4 v[40:43], v186, s[10:11] offset:2048 nt
	global_load_dwordx4 v[44:47], v186, s[10:11] offset:3072 nt
	global_load_dwordx4 v[48:51], v187, s[10:11] offset:0 nt
	global_load_dwordx4 v[52:55], v187, s[10:11] offset:1024 nt
	global_load_dwordx4 v[56:59], v187, s[10:11] offset:2048 nt
	global_load_dwordx4 v[60:63], v187, s[10:11] offset:3072 nt
	s_add_u32 s10, s10, s4
	s_addc_u32 s11, s11, s5
	s_add_u32 s12, s12, s6
	s_addc_u32 s13, s13, s7
	global_load_dwordx2 v[162:163], v188, s[12:13] offset:0
	global_load_dwordx2 v[164:165], v188, s[12:13] offset:512
	global_load_dwordx2 v[166:167], v188, s[12:13] offset:1024
	global_load_dwordx2 v[168:169], v188, s[12:13] offset:1536
	global_load_dwordx2 v[170:171], v188, s[12:13] offset:2048
	global_load_dwordx2 v[172:173], v188, s[12:13] offset:2560
	global_load_dwordx2 v[174:175], v188, s[12:13] offset:3072
	global_load_dwordx2 v[176:177], v188, s[12:13] offset:3584
	global_load_dwordx4 v[130:133], v186, s[10:11] offset:0 nt
	global_load_dwordx4 v[134:137], v186, s[10:11] offset:1024 nt
	global_load_dwordx4 v[138:141], v186, s[10:11] offset:2048 nt
	global_load_dwordx4 v[142:145], v186, s[10:11] offset:3072 nt
	global_load_dwordx4 v[146:149], v187, s[10:11] offset:0 nt
	global_load_dwordx4 v[150:153], v187, s[10:11] offset:1024 nt
	global_load_dwordx4 v[154:157], v187, s[10:11] offset:2048 nt
	global_load_dwordx4 v[158:161], v187, s[10:11] offset:3072 nt
	s_add_u32 s10, s10, s4
	s_addc_u32 s11, s11, s5
	s_add_u32 s12, s12, s6
	s_addc_u32 s13, s13, s7
	s_waitcnt vmcnt(16)
	v_lshlrev_b32_e32 v178, 16, v100
	v_and_b32_e32 v179, 0xffff0000, v100
	v_lshlrev_b32_e32 v180, 16, v101
	v_and_b32_e32 v181, 0xffff0000, v101
	v_pk_add_f32 v[32:33], v[32:33], v[178:179]
	v_pk_add_f32 v[34:35], v[34:35], v[180:181]
	v_pk_mul_f32 v[182:183], v[32:33], v[32:33]
	v_pk_mul_f32 v[184:185], v[34:35], v[34:35]
	v_lshlrev_b32_e32 v178, 16, v102
	v_and_b32_e32 v179, 0xffff0000, v102
	v_lshlrev_b32_e32 v180, 16, v103
	v_and_b32_e32 v181, 0xffff0000, v103
	v_pk_add_f32 v[36:37], v[36:37], v[178:179]
	v_pk_add_f32 v[38:39], v[38:39], v[180:181]
	v_pk_fma_f32 v[182:183], v[36:37], v[36:37], v[182:183]
	v_pk_fma_f32 v[184:185], v[38:39], v[38:39], v[184:185]
	v_lshlrev_b32_e32 v178, 16, v104
	v_and_b32_e32 v179, 0xffff0000, v104
	v_lshlrev_b32_e32 v180, 16, v105
	v_and_b32_e32 v181, 0xffff0000, v105
	v_pk_add_f32 v[40:41], v[40:41], v[178:179]
	v_pk_add_f32 v[42:43], v[42:43], v[180:181]
	v_pk_fma_f32 v[182:183], v[40:41], v[40:41], v[182:183]
	v_pk_fma_f32 v[184:185], v[42:43], v[42:43], v[184:185]
	v_lshlrev_b32_e32 v178, 16, v106
	v_and_b32_e32 v179, 0xffff0000, v106
	v_lshlrev_b32_e32 v180, 16, v107
	v_and_b32_e32 v181, 0xffff0000, v107
	v_pk_add_f32 v[44:45], v[44:45], v[178:179]
	v_pk_add_f32 v[46:47], v[46:47], v[180:181]
	v_pk_fma_f32 v[182:183], v[44:45], v[44:45], v[182:183]
	v_pk_fma_f32 v[184:185], v[46:47], v[46:47], v[184:185]
	v_lshlrev_b32_e32 v178, 16, v108
	v_and_b32_e32 v179, 0xffff0000, v108
	v_lshlrev_b32_e32 v180, 16, v109
	v_and_b32_e32 v181, 0xffff0000, v109
	v_pk_add_f32 v[48:49], v[48:49], v[178:179]
	v_pk_add_f32 v[50:51], v[50:51], v[180:181]
	v_pk_fma_f32 v[182:183], v[48:49], v[48:49], v[182:183]
	v_pk_fma_f32 v[184:185], v[50:51], v[50:51], v[184:185]
	v_lshlrev_b32_e32 v178, 16, v110
	v_and_b32_e32 v179, 0xffff0000, v110
	v_lshlrev_b32_e32 v180, 16, v111
	v_and_b32_e32 v181, 0xffff0000, v111
	v_pk_add_f32 v[52:53], v[52:53], v[178:179]
	v_pk_add_f32 v[54:55], v[54:55], v[180:181]
	v_pk_fma_f32 v[182:183], v[52:53], v[52:53], v[182:183]
	v_pk_fma_f32 v[184:185], v[54:55], v[54:55], v[184:185]
	v_lshlrev_b32_e32 v178, 16, v112
	v_and_b32_e32 v179, 0xffff0000, v112
	v_lshlrev_b32_e32 v180, 16, v113
	v_and_b32_e32 v181, 0xffff0000, v113
	v_pk_add_f32 v[56:57], v[56:57], v[178:179]
	v_pk_add_f32 v[58:59], v[58:59], v[180:181]
	v_pk_fma_f32 v[182:183], v[56:57], v[56:57], v[182:183]
	v_pk_fma_f32 v[184:185], v[58:59], v[58:59], v[184:185]
	v_lshlrev_b32_e32 v178, 16, v114
	v_and_b32_e32 v179, 0xffff0000, v114
	v_lshlrev_b32_e32 v180, 16, v115
	v_and_b32_e32 v181, 0xffff0000, v115
	v_pk_add_f32 v[60:61], v[60:61], v[178:179]
	v_pk_add_f32 v[62:63], v[62:63], v[180:181]
	v_pk_fma_f32 v[182:183], v[60:61], v[60:61], v[182:183]
	v_pk_fma_f32 v[184:185], v[62:63], v[62:63], v[184:185]
	v_pk_add_f32 v[182:183], v[182:183], v[184:185]
	s_nop 0
	v_add_f32_e32 v180, v182, v183
	ds_bpermute_b32 v178, v120, v180
	s_waitcnt lgkmcnt(0)
	v_add_f32_e32 v180, v180, v178
	ds_bpermute_b32 v178, v121, v180
	s_waitcnt lgkmcnt(0)
	v_add_f32_e32 v180, v180, v178
	ds_bpermute_b32 v178, v122, v180
	s_waitcnt lgkmcnt(0)
; __device__ __forceinline__ unsigned pk2_rne(float lo, float hi) { const f32x2_t f = {lo, hi}; return __builtin_bit_cast(unsigned, __builtin_convertvector(f, bf16x2_t)); }
; __device__ __forceinline__ float bflo(unsigned w) { return __uint_as_float(w << 16); }
; __device__ __forceinline__ float bfhi(unsigned w) { return __uint_as_float(w & 0xffff0000u); }
; __device__ __forceinline__ void rows_norm_mod(Ctx& X, const float* src, const bf16_t* delta, float* x1out, const float* w, const float* sc, const float* sh, bf16_t* dst, bool do_cs) {
;     ...
;             for (int j = 0; j < 8; ++j) { const u32x2 d2 = dr[64 * j]; v[j][0] += bflo(d2.x); v[j][1] += bfhi(d2.x); v[j][2] += bflo(d2.y); v[j][3] += bfhi(d2.y); }
;             if (x1out) {
;                 f32x4* xo = (f32x4*)(x1out + (size_t)row * D) + X.lane;
; #pragma unroll
;                 for (int j = 0; j < 8; ++j) xo[64 * j] = v[j];
;             }
;         }
; #pragma unroll
;         for (int j = 0; j < 8; ++j) ss += (v[j][0] * v[j][0] + v[j][1] * v[j][1]) + (v[j][2] * v[j][2] + v[j][3] * v[j][3]);
;         const float r = rsqrtf(wave_sum(ss) * (1.f / D) + EPS);
;         u32x2* o8 = (u32x2*)(dst + (size_t)row * D) + X.lane;
; #pragma unroll
;         for (int j = 0; j < 8; ++j) {
;             const f32x4 y = (v[j] * r) * pa[j] + pb[j];
;             u32x2 p; p.x = pk2_rne(y[0], y[1]); p.y = pk2_rne(y[2], y[3]); o8[64 * j] = p;
;         }
	v_add_f32_e32 v180, v180, v178
	ds_bpermute_b32 v178, v123, v180
	s_waitcnt lgkmcnt(0)
	v_add_f32_e32 v180, v180, v178
	ds_bpermute_b32 v178, v124, v180
	s_waitcnt lgkmcnt(0)
	v_add_f32_e32 v180, v180, v178
	ds_bpermute_b32 v178, v125, v180
	s_waitcnt lgkmcnt(0)
	v_add_f32_e32 v180, v180, v178
	v_fmamk_f32 v180, v180, 0x3a000000, v126
	v_mul_f32_e32 v178, 0x4b800000, v180
	v_cmp_gt_f32_e32 vcc, s2, v180
	s_nop 1
	v_cndmask_b32_e32 v180, v180, v178, vcc
	v_rsq_f32_e32 v180, v180
	s_nop 0
	v_mul_f32_e32 v178, 0x45800000, v180
	v_cndmask_b32_e32 v178, v180, v178, vcc
	v_pk_mul_f32 v[32:33], v[32:33], v[178:179] op_sel_hi:[1,0]
	v_pk_mul_f32 v[34:35], v[34:35], v[178:179] op_sel_hi:[1,0]
	v_pk_mul_f32 v[36:37], v[36:37], v[178:179] op_sel_hi:[1,0]
	v_pk_mul_f32 v[38:39], v[38:39], v[178:179] op_sel_hi:[1,0]
	v_pk_mul_f32 v[40:41], v[40:41], v[178:179] op_sel_hi:[1,0]
	v_pk_mul_f32 v[42:43], v[42:43], v[178:179] op_sel_hi:[1,0]
	v_pk_mul_f32 v[44:45], v[44:45], v[178:179] op_sel_hi:[1,0]
	v_pk_mul_f32 v[46:47], v[46:47], v[178:179] op_sel_hi:[1,0]
	v_pk_mul_f32 v[48:49], v[48:49], v[178:179] op_sel_hi:[1,0]
	v_pk_mul_f32 v[50:51], v[50:51], v[178:179] op_sel_hi:[1,0]
	v_pk_mul_f32 v[52:53], v[52:53], v[178:179] op_sel_hi:[1,0]
	v_pk_mul_f32 v[54:55], v[54:55], v[178:179] op_sel_hi:[1,0]
	v_pk_mul_f32 v[56:57], v[56:57], v[178:179] op_sel_hi:[1,0]
	v_pk_mul_f32 v[58:59], v[58:59], v[178:179] op_sel_hi:[1,0]
	v_pk_mul_f32 v[60:61], v[60:61], v[178:179] op_sel_hi:[1,0]
	v_pk_mul_f32 v[62:63], v[62:63], v[178:179] op_sel_hi:[1,0]
	v_pk_fma_f32 v[32:33], v[66:67], v[32:33], v[0:1]
	v_pk_fma_f32 v[34:35], v[64:65], v[34:35], v[2:3]
	v_pk_fma_f32 v[36:37], v[70:71], v[36:37], v[4:5]
	v_pk_fma_f32 v[38:39], v[68:69], v[38:39], v[6:7]
	v_pk_fma_f32 v[40:41], v[74:75], v[40:41], v[8:9]
	v_pk_fma_f32 v[42:43], v[72:73], v[42:43], v[10:11]
	v_pk_fma_f32 v[44:45], v[78:79], v[44:45], v[12:13]
	v_pk_fma_f32 v[46:47], v[76:77], v[46:47], v[14:15]
	v_pk_fma_f32 v[48:49], v[82:83], v[48:49], v[16:17]
	v_pk_fma_f32 v[50:51], v[80:81], v[50:51], v[18:19]
	v_pk_fma_f32 v[52:53], v[86:87], v[52:53], v[20:21]
	v_pk_fma_f32 v[54:55], v[84:85], v[54:55], v[22:23]
	v_pk_fma_f32 v[56:57], v[90:91], v[56:57], v[24:25]
	v_pk_fma_f32 v[58:59], v[88:89], v[58:59], v[26:27]
	v_pk_fma_f32 v[60:61], v[94:95], v[60:61], v[28:29]
	v_pk_fma_f32 v[62:63], v[92:93], v[62:63], v[30:31]
	v_cvt_pk_bf16_f32 v32, v32, v33
	v_cvt_pk_bf16_f32 v33, v34, v35
	v_cvt_pk_bf16_f32 v36, v36, v37
	v_cvt_pk_bf16_f32 v37, v38, v39
	v_cvt_pk_bf16_f32 v40, v40, v41
	v_cvt_pk_bf16_f32 v41, v42, v43
	v_cvt_pk_bf16_f32 v44, v44, v45
	v_cvt_pk_bf16_f32 v45, v46, v47
	v_cvt_pk_bf16_f32 v48, v48, v49
	v_cvt_pk_bf16_f32 v49, v50, v51
	v_cvt_pk_bf16_f32 v52, v52, v53
	v_cvt_pk_bf16_f32 v53, v54, v55
	v_cvt_pk_bf16_f32 v56, v56, v57
	v_cvt_pk_bf16_f32 v57, v58, v59
	v_cvt_pk_bf16_f32 v60, v60, v61
	v_cvt_pk_bf16_f32 v61, v62, v63
	global_store_dwordx2 v188, v[32:33], s[14:15] offset:0
	global_store_dwordx2 v188, v[36:37], s[14:15] offset:512
	global_store_dwordx2 v188, v[40:41], s[14:15] offset:1024
	global_store_dwordx2 v188, v[44:45], s[14:15] offset:1536
	global_store_dwordx2 v188, v[48:49], s[14:15] offset:2048
	global_store_dwordx2 v188, v[52:53], s[14:15] offset:2560
	global_store_dwordx2 v188, v[56:57], s[14:15] offset:3072
	global_store_dwordx2 v188, v[60:61], s[14:15] offset:3584
	s_add_u32 s14, s14, s6
	s_addc_u32 s15, s15, s7
	global_load_dwordx2 v[100:101], v188, s[12:13] offset:0
	global_load_dwordx2 v[102:103], v188, s[12:13] offset:512
	global_load_dwordx2 v[104:105], v188, s[12:13] offset:1024
	global_load_dwordx2 v[106:107], v188, s[12:13] offset:1536
	global_load_dwordx2 v[108:109], v188, s[12:13] offset:2048
	global_load_dwordx2 v[110:111], v188, s[12:13] offset:2560
	global_load_dwordx2 v[112:113], v188, s[12:13] offset:3072
	global_load_dwordx2 v[114:115], v188, s[12:13] offset:3584
	global_load_dwordx4 v[32:35], v186, s[10:11] offset:0 nt
	global_load_dwordx4 v[36:39], v186, s[10:11] offset:1024 nt
	global_load_dwordx4 v[40:43], v186, s[10:11] offset:2048 nt
	global_load_dwordx4 v[44:47], v186, s[10:11] offset:3072 nt
	global_load_dwordx4 v[48:51], v187, s[10:11] offset:0 nt
	global_load_dwordx4 v[52:55], v187, s[10:11] offset:1024 nt
	global_load_dwordx4 v[56:59], v187, s[10:11] offset:2048 nt
	global_load_dwordx4 v[60:63], v187, s[10:11] offset:3072 nt
	s_add_u32 s10, s10, s4
	s_addc_u32 s11, s11, s5
	s_add_u32 s12, s12, s6
	s_addc_u32 s13, s13, s7
	s_waitcnt vmcnt(24)
; __device__ __forceinline__ float bflo(unsigned w) { return __uint_as_float(w << 16); }
; __device__ __forceinline__ float bfhi(unsigned w) { return __uint_as_float(w & 0xffff0000u); }
; __device__ __forceinline__ void rows_norm_mod(Ctx& X, const float* src, const bf16_t* delta, float* x1out, const float* w, const float* sc, const float* sh, bf16_t* dst, bool do_cs) {
;     ...
;             for (int j = 0; j < 8; ++j) { const u32x2 d2 = dr[64 * j]; v[j][0] += bflo(d2.x); v[j][1] += bfhi(d2.x); v[j][2] += bflo(d2.y); v[j][3] += bfhi(d2.y); }
;             if (x1out) {
;                 f32x4* xo = (f32x4*)(x1out + (size_t)row * D) + X.lane;
; #pragma unroll
;                 for (int j = 0; j < 8; ++j) xo[64 * j] = v[j];
;             }
;         }
; #pragma unroll
;         for (int j = 0; j < 8; ++j) ss += (v[j][0] * v[j][0] + v[j][1] * v[j][1]) + (v[j][2] * v[j][2] + v[j][3] * v[j][3]);
;         const float r = rsqrtf(wave_sum(ss) * (1.f / D) + EPS);
;         u32x2* o8 = (u32x2*)(dst + (size_t)row * D) + X.lane;
; #pragma unroll
;         for (int j = 0; j < 8; ++j) {
;             const f32x4 y = (v[j] * r) * pa[j] + pb[j];
	v_lshlrev_b32_e32 v178, 16, v162
	v_and_b32_e32 v179, 0xffff0000, v162
	v_lshlrev_b32_e32 v180, 16, v163
	v_and_b32_e32 v181, 0xffff0000, v163
	v_pk_add_f32 v[130:131], v[130:131], v[178:179]
	v_pk_add_f32 v[132:133], v[132:133], v[180:181]
	v_pk_mul_f32 v[182:183], v[130:131], v[130:131]
	v_pk_mul_f32 v[184:185], v[132:133], v[132:133]
	v_lshlrev_b32_e32 v178, 16, v164
	v_and_b32_e32 v179, 0xffff0000, v164
	v_lshlrev_b32_e32 v180, 16, v165
	v_and_b32_e32 v181, 0xffff0000, v165
	v_pk_add_f32 v[134:135], v[134:135], v[178:179]
	v_pk_add_f32 v[136:137], v[136:137], v[180:181]
	v_pk_fma_f32 v[182:183], v[134:135], v[134:135], v[182:183]
	v_pk_fma_f32 v[184:185], v[136:137], v[136:137], v[184:185]
	v_lshlrev_b32_e32 v178, 16, v166
	v_and_b32_e32 v179, 0xffff0000, v166
	v_lshlrev_b32_e32 v180, 16, v167
	v_and_b32_e32 v181, 0xffff0000, v167
	v_pk_add_f32 v[138:139], v[138:139], v[178:179]
	v_pk_add_f32 v[140:141], v[140:141], v[180:181]
	v_pk_fma_f32 v[182:183], v[138:139], v[138:139], v[182:183]
	v_pk_fma_f32 v[184:185], v[140:141], v[140:141], v[184:185]
	v_lshlrev_b32_e32 v178, 16, v168
	v_and_b32_e32 v179, 0xffff0000, v168
	v_lshlrev_b32_e32 v180, 16, v169
	v_and_b32_e32 v181, 0xffff0000, v169
	v_pk_add_f32 v[142:143], v[142:143], v[178:179]
	v_pk_add_f32 v[144:145], v[144:145], v[180:181]
	v_pk_fma_f32 v[182:183], v[142:143], v[142:143], v[182:183]
	v_pk_fma_f32 v[184:185], v[144:145], v[144:145], v[184:185]
	v_lshlrev_b32_e32 v178, 16, v170
	v_and_b32_e32 v179, 0xffff0000, v170
	v_lshlrev_b32_e32 v180, 16, v171
	v_and_b32_e32 v181, 0xffff0000, v171
	v_pk_add_f32 v[146:147], v[146:147], v[178:179]
	v_pk_add_f32 v[148:149], v[148:149], v[180:181]
	v_pk_fma_f32 v[182:183], v[146:147], v[146:147], v[182:183]
	v_pk_fma_f32 v[184:185], v[148:149], v[148:149], v[184:185]
	v_lshlrev_b32_e32 v178, 16, v172
	v_and_b32_e32 v179, 0xffff0000, v172
	v_lshlrev_b32_e32 v180, 16, v173
	v_and_b32_e32 v181, 0xffff0000, v173
	v_pk_add_f32 v[150:151], v[150:151], v[178:179]
	v_pk_add_f32 v[152:153], v[152:153], v[180:181]
	v_pk_fma_f32 v[182:183], v[150:151], v[150:151], v[182:183]
	v_pk_fma_f32 v[184:185], v[152:153], v[152:153], v[184:185]
	v_lshlrev_b32_e32 v178, 16, v174
	v_and_b32_e32 v179, 0xffff0000, v174
	v_lshlrev_b32_e32 v180, 16, v175
	v_and_b32_e32 v181, 0xffff0000, v175
	v_pk_add_f32 v[154:155], v[154:155], v[178:179]
	v_pk_add_f32 v[156:157], v[156:157], v[180:181]
	v_pk_fma_f32 v[182:183], v[154:155], v[154:155], v[182:183]
	v_pk_fma_f32 v[184:185], v[156:157], v[156:157], v[184:185]
	v_lshlrev_b32_e32 v178, 16, v176
	v_and_b32_e32 v179, 0xffff0000, v176
	v_lshlrev_b32_e32 v180, 16, v177
	v_and_b32_e32 v181, 0xffff0000, v177
	v_pk_add_f32 v[158:159], v[158:159], v[178:179]
	v_pk_add_f32 v[160:161], v[160:161], v[180:181]
	v_pk_fma_f32 v[182:183], v[158:159], v[158:159], v[182:183]
	v_pk_fma_f32 v[184:185], v[160:161], v[160:161], v[184:185]
	v_pk_add_f32 v[182:183], v[182:183], v[184:185]
	s_nop 0
	v_add_f32_e32 v180, v182, v183
	ds_bpermute_b32 v178, v120, v180
	s_waitcnt lgkmcnt(0)
	v_add_f32_e32 v180, v180, v178
	ds_bpermute_b32 v178, v121, v180
	s_waitcnt lgkmcnt(0)
	v_add_f32_e32 v180, v180, v178
	ds_bpermute_b32 v178, v122, v180
	s_waitcnt lgkmcnt(0)
	v_add_f32_e32 v180, v180, v178
	ds_bpermute_b32 v178, v123, v180
	s_waitcnt lgkmcnt(0)
	v_add_f32_e32 v180, v180, v178
	ds_bpermute_b32 v178, v124, v180
	s_waitcnt lgkmcnt(0)
	v_add_f32_e32 v180, v180, v178
	ds_bpermute_b32 v178, v125, v180
	s_waitcnt lgkmcnt(0)
	v_add_f32_e32 v180, v180, v178
	v_fmamk_f32 v180, v180, 0x3a000000, v126
	v_mul_f32_e32 v178, 0x4b800000, v180
	v_cmp_gt_f32_e32 vcc, s2, v180
	s_nop 1
	v_cndmask_b32_e32 v180, v180, v178, vcc
	v_rsq_f32_e32 v180, v180
	s_nop 0
	v_mul_f32_e32 v178, 0x45800000, v180
	v_cndmask_b32_e32 v178, v180, v178, vcc
	v_pk_mul_f32 v[130:131], v[130:131], v[178:179] op_sel_hi:[1,0]
	v_pk_mul_f32 v[132:133], v[132:133], v[178:179] op_sel_hi:[1,0]
	v_pk_mul_f32 v[134:135], v[134:135], v[178:179] op_sel_hi:[1,0]
	v_pk_mul_f32 v[136:137], v[136:137], v[178:179] op_sel_hi:[1,0]
	v_pk_mul_f32 v[138:139], v[138:139], v[178:179] op_sel_hi:[1,0]
	v_pk_mul_f32 v[140:141], v[140:141], v[178:179] op_sel_hi:[1,0]
	v_pk_mul_f32 v[142:143], v[142:143], v[178:179] op_sel_hi:[1,0]
	v_pk_mul_f32 v[144:145], v[144:145], v[178:179] op_sel_hi:[1,0]
	v_pk_mul_f32 v[146:147], v[146:147], v[178:179] op_sel_hi:[1,0]
	v_pk_mul_f32 v[148:149], v[148:149], v[178:179] op_sel_hi:[1,0]
	v_pk_mul_f32 v[150:151], v[150:151], v[178:179] op_sel_hi:[1,0]
	v_pk_mul_f32 v[152:153], v[152:153], v[178:179] op_sel_hi:[1,0]
	v_pk_mul_f32 v[154:155], v[154:155], v[178:179] op_sel_hi:[1,0]
	v_pk_mul_f32 v[156:157], v[156:157], v[178:179] op_sel_hi:[1,0]
	v_pk_mul_f32 v[158:159], v[158:159], v[178:179] op_sel_hi:[1,0]
	v_pk_mul_f32 v[160:161], v[160:161], v[178:179] op_sel_hi:[1,0]
	v_pk_fma_f32 v[130:131], v[66:67], v[130:131], v[0:1]
	v_pk_fma_f32 v[132:133], v[64:65], v[132:133], v[2:3]
	v_pk_fma_f32 v[134:135], v[70:71], v[134:135], v[4:5]
	v_pk_fma_f32 v[136:137], v[68:69], v[136:137], v[6:7]
	v_pk_fma_f32 v[138:139], v[74:75], v[138:139], v[8:9]
	v_pk_fma_f32 v[140:141], v[72:73], v[140:141], v[10:11]
	v_pk_fma_f32 v[142:143], v[78:79], v[142:143], v[12:13]
	v_pk_fma_f32 v[144:145], v[76:77], v[144:145], v[14:15]
	v_pk_fma_f32 v[146:147], v[82:83], v[146:147], v[16:17]
	v_pk_fma_f32 v[148:149], v[80:81], v[148:149], v[18:19]
	v_pk_fma_f32 v[150:151], v[86:87], v[150:151], v[20:21]
	v_pk_fma_f32 v[152:153], v[84:85], v[152:153], v[22:23]
	v_pk_fma_f32 v[154:155], v[90:91], v[154:155], v[24:25]
	v_pk_fma_f32 v[156:157], v[88:89], v[156:157], v[26:27]
	v_pk_fma_f32 v[158:159], v[94:95], v[158:159], v[28:29]
; __device__ __forceinline__ unsigned pk2_rne(float lo, float hi) { const f32x2_t f = {lo, hi}; return __builtin_bit_cast(unsigned, __builtin_convertvector(f, bf16x2_t)); }
; __device__ __forceinline__ float bflo(unsigned w) { return __uint_as_float(w << 16); }
; __device__ __forceinline__ float bfhi(unsigned w) { return __uint_as_float(w & 0xffff0000u); }
; __device__ __forceinline__ void rows_norm_mod(Ctx& X, const float* src, const bf16_t* delta, float* x1out, const float* w, const float* sc, const float* sh, bf16_t* dst, bool do_cs) {
;     ...
;     for (int row = X.gw; row < S; row += X.NGW) {
;         const f32x4* xr = (const f32x4*)(src + (size_t)row * D) + X.lane;
;         f32x4 v[8]; float ss = 0.f;
; #pragma unroll
;         for (int j = 0; j < 8; ++j) v[j] = __builtin_nontemporal_load(xr + 64 * j);
;         if (delta) {
;             const u32x2* dr = (const u32x2*)(delta + (size_t)row * D) + X.lane;
; #pragma unroll
;             for (int j = 0; j < 8; ++j) { const u32x2 d2 = dr[64 * j]; v[j][0] += bflo(d2.x); v[j][1] += bfhi(d2.x); v[j][2] += bflo(d2.y); v[j][3] += bfhi(d2.y); }
;             if (x1out) {
;                 f32x4* xo = (f32x4*)(x1out + (size_t)row * D) + X.lane;
; #pragma unroll
;                 for (int j = 0; j < 8; ++j) xo[64 * j] = v[j];
;             }
;         }
; #pragma unroll
;         for (int j = 0; j < 8; ++j) ss += (v[j][0] * v[j][0] + v[j][1] * v[j][1]) + (v[j][2] * v[j][2] + v[j][3] * v[j][3]);
;         const float r = rsqrtf(wave_sum(ss) * (1.f / D) + EPS);
;         u32x2* o8 = (u32x2*)(dst + (size_t)row * D) + X.lane;
; #pragma unroll
;         for (int j = 0; j < 8; ++j) {
;             const f32x4 y = (v[j] * r) * pa[j] + pb[j];
;             u32x2 p; p.x = pk2_rne(y[0], y[1]); p.y = pk2_rne(y[2], y[3]); o8[64 * j] = p;
;         }
	v_pk_fma_f32 v[160:161], v[92:93], v[160:161], v[30:31]
	v_cvt_pk_bf16_f32 v130, v130, v131
	v_cvt_pk_bf16_f32 v131, v132, v133
	v_cvt_pk_bf16_f32 v134, v134, v135
	v_cvt_pk_bf16_f32 v135, v136, v137
	v_cvt_pk_bf16_f32 v138, v138, v139
	v_cvt_pk_bf16_f32 v139, v140, v141
	v_cvt_pk_bf16_f32 v142, v142, v143
	v_cvt_pk_bf16_f32 v143, v144, v145
	v_cvt_pk_bf16_f32 v146, v146, v147
	v_cvt_pk_bf16_f32 v147, v148, v149
	v_cvt_pk_bf16_f32 v150, v150, v151
	v_cvt_pk_bf16_f32 v151, v152, v153
	v_cvt_pk_bf16_f32 v154, v154, v155
	v_cvt_pk_bf16_f32 v155, v156, v157
	v_cvt_pk_bf16_f32 v158, v158, v159
	v_cvt_pk_bf16_f32 v159, v160, v161
	global_store_dwordx2 v188, v[130:131], s[14:15] offset:0
	global_store_dwordx2 v188, v[134:135], s[14:15] offset:512
	global_store_dwordx2 v188, v[138:139], s[14:15] offset:1024
	global_store_dwordx2 v188, v[142:143], s[14:15] offset:1536
	global_store_dwordx2 v188, v[146:147], s[14:15] offset:2048
	global_store_dwordx2 v188, v[150:151], s[14:15] offset:2560
	global_store_dwordx2 v188, v[154:155], s[14:15] offset:3072
	global_store_dwordx2 v188, v[158:159], s[14:15] offset:3584
	s_add_u32 s14, s14, s6
	s_addc_u32 s15, s15, s7
	global_load_dwordx2 v[162:163], v188, s[12:13] offset:0
	global_load_dwordx2 v[164:165], v188, s[12:13] offset:512
	global_load_dwordx2 v[166:167], v188, s[12:13] offset:1024
	global_load_dwordx2 v[168:169], v188, s[12:13] offset:1536
	global_load_dwordx2 v[170:171], v188, s[12:13] offset:2048
	global_load_dwordx2 v[172:173], v188, s[12:13] offset:2560
	global_load_dwordx2 v[174:175], v188, s[12:13] offset:3072
	global_load_dwordx2 v[176:177], v188, s[12:13] offset:3584
	global_load_dwordx4 v[130:133], v186, s[10:11] offset:0 nt
	global_load_dwordx4 v[134:137], v186, s[10:11] offset:1024 nt
	global_load_dwordx4 v[138:141], v186, s[10:11] offset:2048 nt
	global_load_dwordx4 v[142:145], v186, s[10:11] offset:3072 nt
	global_load_dwordx4 v[146:149], v187, s[10:11] offset:0 nt
	global_load_dwordx4 v[150:153], v187, s[10:11] offset:1024 nt
	global_load_dwordx4 v[154:157], v187, s[10:11] offset:2048 nt
	global_load_dwordx4 v[158:161], v187, s[10:11] offset:3072 nt
	s_add_u32 s10, s10, s4
	s_addc_u32 s11, s11, s5
	s_add_u32 s12, s12, s6
	s_addc_u32 s13, s13, s7
	s_waitcnt vmcnt(24)
	v_lshlrev_b32_e32 v178, 16, v100
	v_and_b32_e32 v179, 0xffff0000, v100
	v_lshlrev_b32_e32 v180, 16, v101
	v_and_b32_e32 v181, 0xffff0000, v101
	v_pk_add_f32 v[32:33], v[32:33], v[178:179]
	v_pk_add_f32 v[34:35], v[34:35], v[180:181]
	v_pk_mul_f32 v[182:183], v[32:33], v[32:33]
	v_pk_mul_f32 v[184:185], v[34:35], v[34:35]
	v_lshlrev_b32_e32 v178, 16, v102
	v_and_b32_e32 v179, 0xffff0000, v102
	v_lshlrev_b32_e32 v180, 16, v103
	v_and_b32_e32 v181, 0xffff0000, v103
	v_pk_add_f32 v[36:37], v[36:37], v[178:179]
	v_pk_add_f32 v[38:39], v[38:39], v[180:181]
	v_pk_fma_f32 v[182:183], v[36:37], v[36:37], v[182:183]
	v_pk_fma_f32 v[184:185], v[38:39], v[38:39], v[184:185]
	v_lshlrev_b32_e32 v178, 16, v104
	v_and_b32_e32 v179, 0xffff0000, v104
	v_lshlrev_b32_e32 v180, 16, v105
	v_and_b32_e32 v181, 0xffff0000, v105
	v_pk_add_f32 v[40:41], v[40:41], v[178:179]
	v_pk_add_f32 v[42:43], v[42:43], v[180:181]
	v_pk_fma_f32 v[182:183], v[40:41], v[40:41], v[182:183]
	v_pk_fma_f32 v[184:185], v[42:43], v[42:43], v[184:185]
	v_lshlrev_b32_e32 v178, 16, v106
	v_and_b32_e32 v179, 0xffff0000, v106
	v_lshlrev_b32_e32 v180, 16, v107
	v_and_b32_e32 v181, 0xffff0000, v107
	v_pk_add_f32 v[44:45], v[44:45], v[178:179]
	v_pk_add_f32 v[46:47], v[46:47], v[180:181]
	v_pk_fma_f32 v[182:183], v[44:45], v[44:45], v[182:183]
	v_pk_fma_f32 v[184:185], v[46:47], v[46:47], v[184:185]
	v_lshlrev_b32_e32 v178, 16, v108
	v_and_b32_e32 v179, 0xffff0000, v108
	v_lshlrev_b32_e32 v180, 16, v109
	v_and_b32_e32 v181, 0xffff0000, v109
	v_pk_add_f32 v[48:49], v[48:49], v[178:179]
	v_pk_add_f32 v[50:51], v[50:51], v[180:181]
	v_pk_fma_f32 v[182:183], v[48:49], v[48:49], v[182:183]
	v_pk_fma_f32 v[184:185], v[50:51], v[50:51], v[184:185]
	v_lshlrev_b32_e32 v178, 16, v110
	v_and_b32_e32 v179, 0xffff0000, v110
	v_lshlrev_b32_e32 v180, 16, v111
	v_and_b32_e32 v181, 0xffff0000, v111
	v_pk_add_f32 v[52:53], v[52:53], v[178:179]
	v_pk_add_f32 v[54:55], v[54:55], v[180:181]
	v_pk_fma_f32 v[182:183], v[52:53], v[52:53], v[182:183]
	v_pk_fma_f32 v[184:185], v[54:55], v[54:55], v[184:185]
	v_lshlrev_b32_e32 v178, 16, v112
	v_and_b32_e32 v179, 0xffff0000, v112
	v_lshlrev_b32_e32 v180, 16, v113
	v_and_b32_e32 v181, 0xffff0000, v113
	v_pk_add_f32 v[56:57], v[56:57], v[178:179]
	v_pk_add_f32 v[58:59], v[58:59], v[180:181]
	v_pk_fma_f32 v[182:183], v[56:57], v[56:57], v[182:183]
	v_pk_fma_f32 v[184:185], v[58:59], v[58:59], v[184:185]
	v_lshlrev_b32_e32 v178, 16, v114
	v_and_b32_e32 v179, 0xffff0000, v114
	v_lshlrev_b32_e32 v180, 16, v115
	v_and_b32_e32 v181, 0xffff0000, v115
	v_pk_add_f32 v[60:61], v[60:61], v[178:179]
	v_pk_add_f32 v[62:63], v[62:63], v[180:181]
	v_pk_fma_f32 v[182:183], v[60:61], v[60:61], v[182:183]
	v_pk_fma_f32 v[184:185], v[62:63], v[62:63], v[184:185]
	v_pk_add_f32 v[182:183], v[182:183], v[184:185]
	s_nop 0
	v_add_f32_e32 v180, v182, v183
	ds_bpermute_b32 v178, v120, v180
	s_waitcnt lgkmcnt(0)
	v_add_f32_e32 v180, v180, v178
	ds_bpermute_b32 v178, v121, v180
	s_waitcnt lgkmcnt(0)
	v_add_f32_e32 v180, v180, v178
	ds_bpermute_b32 v178, v122, v180
	s_waitcnt lgkmcnt(0)
	v_add_f32_e32 v180, v180, v178
	ds_bpermute_b32 v178, v123, v180
	s_waitcnt lgkmcnt(0)
	v_add_f32_e32 v180, v180, v178
	ds_bpermute_b32 v178, v124, v180
	s_waitcnt lgkmcnt(0)
	v_add_f32_e32 v180, v180, v178
	ds_bpermute_b32 v178, v125, v180
	s_waitcnt lgkmcnt(0)
; __device__ __forceinline__ unsigned pk2_rne(float lo, float hi) { const f32x2_t f = {lo, hi}; return __builtin_bit_cast(unsigned, __builtin_convertvector(f, bf16x2_t)); }
; __device__ __forceinline__ float bflo(unsigned w) { return __uint_as_float(w << 16); }
; __device__ __forceinline__ float bfhi(unsigned w) { return __uint_as_float(w & 0xffff0000u); }
; __device__ __forceinline__ void rows_norm_mod(Ctx& X, const float* src, const bf16_t* delta, float* x1out, const float* w, const float* sc, const float* sh, bf16_t* dst, bool do_cs) {
;     ...
;         const f32x4* xr = (const f32x4*)(src + (size_t)row * D) + X.lane;
;         f32x4 v[8]; float ss = 0.f;
; #pragma unroll
;         for (int j = 0; j < 8; ++j) v[j] = __builtin_nontemporal_load(xr + 64 * j);
;         if (delta) {
;             const u32x2* dr = (const u32x2*)(delta + (size_t)row * D) + X.lane;
; #pragma unroll
;             for (int j = 0; j < 8; ++j) { const u32x2 d2 = dr[64 * j]; v[j][0] += bflo(d2.x); v[j][1] += bfhi(d2.x); v[j][2] += bflo(d2.y); v[j][3] += bfhi(d2.y); }
;     ...
;         const float r = rsqrtf(wave_sum(ss) * (1.f / D) + EPS);
;         u32x2* o8 = (u32x2*)(dst + (size_t)row * D) + X.lane;
; #pragma unroll
;         for (int j = 0; j < 8; ++j) {
;             const f32x4 y = (v[j] * r) * pa[j] + pb[j];
;             u32x2 p; p.x = pk2_rne(y[0], y[1]); p.y = pk2_rne(y[2], y[3]); o8[64 * j] = p;
;         }
	v_add_f32_e32 v180, v180, v178
	v_fmamk_f32 v180, v180, 0x3a000000, v126
	v_mul_f32_e32 v178, 0x4b800000, v180
	v_cmp_gt_f32_e32 vcc, s2, v180
	s_nop 1
	v_cndmask_b32_e32 v180, v180, v178, vcc
	v_rsq_f32_e32 v180, v180
	s_nop 0
	v_mul_f32_e32 v178, 0x45800000, v180
	v_cndmask_b32_e32 v178, v180, v178, vcc
	v_pk_mul_f32 v[32:33], v[32:33], v[178:179] op_sel_hi:[1,0]
	v_pk_mul_f32 v[34:35], v[34:35], v[178:179] op_sel_hi:[1,0]
	v_pk_mul_f32 v[36:37], v[36:37], v[178:179] op_sel_hi:[1,0]
	v_pk_mul_f32 v[38:39], v[38:39], v[178:179] op_sel_hi:[1,0]
	v_pk_mul_f32 v[40:41], v[40:41], v[178:179] op_sel_hi:[1,0]
	v_pk_mul_f32 v[42:43], v[42:43], v[178:179] op_sel_hi:[1,0]
	v_pk_mul_f32 v[44:45], v[44:45], v[178:179] op_sel_hi:[1,0]
	v_pk_mul_f32 v[46:47], v[46:47], v[178:179] op_sel_hi:[1,0]
	v_pk_mul_f32 v[48:49], v[48:49], v[178:179] op_sel_hi:[1,0]
	v_pk_mul_f32 v[50:51], v[50:51], v[178:179] op_sel_hi:[1,0]
	v_pk_mul_f32 v[52:53], v[52:53], v[178:179] op_sel_hi:[1,0]
	v_pk_mul_f32 v[54:55], v[54:55], v[178:179] op_sel_hi:[1,0]
	v_pk_mul_f32 v[56:57], v[56:57], v[178:179] op_sel_hi:[1,0]
	v_pk_mul_f32 v[58:59], v[58:59], v[178:179] op_sel_hi:[1,0]
	v_pk_mul_f32 v[60:61], v[60:61], v[178:179] op_sel_hi:[1,0]
	v_pk_mul_f32 v[62:63], v[62:63], v[178:179] op_sel_hi:[1,0]
	v_pk_fma_f32 v[32:33], v[66:67], v[32:33], v[0:1]
	v_pk_fma_f32 v[34:35], v[64:65], v[34:35], v[2:3]
	v_pk_fma_f32 v[36:37], v[70:71], v[36:37], v[4:5]
	v_pk_fma_f32 v[38:39], v[68:69], v[38:39], v[6:7]
	v_pk_fma_f32 v[40:41], v[74:75], v[40:41], v[8:9]
	v_pk_fma_f32 v[42:43], v[72:73], v[42:43], v[10:11]
	v_pk_fma_f32 v[44:45], v[78:79], v[44:45], v[12:13]
	v_pk_fma_f32 v[46:47], v[76:77], v[46:47], v[14:15]
	v_pk_fma_f32 v[48:49], v[82:83], v[48:49], v[16:17]
	v_pk_fma_f32 v[50:51], v[80:81], v[50:51], v[18:19]
	v_pk_fma_f32 v[52:53], v[86:87], v[52:53], v[20:21]
	v_pk_fma_f32 v[54:55], v[84:85], v[54:55], v[22:23]
	v_pk_fma_f32 v[56:57], v[90:91], v[56:57], v[24:25]
	v_pk_fma_f32 v[58:59], v[88:89], v[58:59], v[26:27]
	v_pk_fma_f32 v[60:61], v[94:95], v[60:61], v[28:29]
	v_pk_fma_f32 v[62:63], v[92:93], v[62:63], v[30:31]
	v_cvt_pk_bf16_f32 v32, v32, v33
	v_cvt_pk_bf16_f32 v33, v34, v35
	v_cvt_pk_bf16_f32 v36, v36, v37
	v_cvt_pk_bf16_f32 v37, v38, v39
	v_cvt_pk_bf16_f32 v40, v40, v41
	v_cvt_pk_bf16_f32 v41, v42, v43
	v_cvt_pk_bf16_f32 v44, v44, v45
	v_cvt_pk_bf16_f32 v45, v46, v47
	v_cvt_pk_bf16_f32 v48, v48, v49
	v_cvt_pk_bf16_f32 v49, v50, v51
	v_cvt_pk_bf16_f32 v52, v52, v53
	v_cvt_pk_bf16_f32 v53, v54, v55
	v_cvt_pk_bf16_f32 v56, v56, v57
	v_cvt_pk_bf16_f32 v57, v58, v59
	v_cvt_pk_bf16_f32 v60, v60, v61
	v_cvt_pk_bf16_f32 v61, v62, v63
	global_store_dwordx2 v188, v[32:33], s[14:15] offset:0
	global_store_dwordx2 v188, v[36:37], s[14:15] offset:512
	global_store_dwordx2 v188, v[40:41], s[14:15] offset:1024
	global_store_dwordx2 v188, v[44:45], s[14:15] offset:1536
	global_store_dwordx2 v188, v[48:49], s[14:15] offset:2048
	global_store_dwordx2 v188, v[52:53], s[14:15] offset:2560
	global_store_dwordx2 v188, v[56:57], s[14:15] offset:3072
	global_store_dwordx2 v188, v[60:61], s[14:15] offset:3584
	s_add_u32 s14, s14, s6
	s_addc_u32 s15, s15, s7
	global_load_dwordx2 v[100:101], v188, s[12:13] offset:0
	global_load_dwordx2 v[102:103], v188, s[12:13] offset:512
	global_load_dwordx2 v[104:105], v188, s[12:13] offset:1024
	global_load_dwordx2 v[106:107], v188, s[12:13] offset:1536
	global_load_dwordx2 v[108:109], v188, s[12:13] offset:2048
	global_load_dwordx2 v[110:111], v188, s[12:13] offset:2560
	global_load_dwordx2 v[112:113], v188, s[12:13] offset:3072
	global_load_dwordx2 v[114:115], v188, s[12:13] offset:3584
	global_load_dwordx4 v[32:35], v186, s[10:11] offset:0 nt
	global_load_dwordx4 v[36:39], v186, s[10:11] offset:1024 nt
	global_load_dwordx4 v[40:43], v186, s[10:11] offset:2048 nt
	global_load_dwordx4 v[44:47], v186, s[10:11] offset:3072 nt
	global_load_dwordx4 v[48:51], v187, s[10:11] offset:0 nt
	global_load_dwordx4 v[52:55], v187, s[10:11] offset:1024 nt
	global_load_dwordx4 v[56:59], v187, s[10:11] offset:2048 nt
	global_load_dwordx4 v[60:63], v187, s[10:11] offset:3072 nt
	s_add_u32 s10, s10, s4
	s_addc_u32 s11, s11, s5
	s_add_u32 s12, s12, s6
	s_addc_u32 s13, s13, s7
	s_waitcnt vmcnt(24)
; __device__ __forceinline__ float bflo(unsigned w) { return __uint_as_float(w << 16); }
; __device__ __forceinline__ float bfhi(unsigned w) { return __uint_as_float(w & 0xffff0000u); }
; __device__ __forceinline__ void rows_norm_mod(Ctx& X, const float* src, const bf16_t* delta, float* x1out, const float* w, const float* sc, const float* sh, bf16_t* dst, bool do_cs) {
;     ...
;             for (int j = 0; j < 8; ++j) { const u32x2 d2 = dr[64 * j]; v[j][0] += bflo(d2.x); v[j][1] += bfhi(d2.x); v[j][2] += bflo(d2.y); v[j][3] += bfhi(d2.y); }
;             if (x1out) {
;                 f32x4* xo = (f32x4*)(x1out + (size_t)row * D) + X.lane;
; #pragma unroll
;                 for (int j = 0; j < 8; ++j) xo[64 * j] = v[j];
;             }
;         }
; #pragma unroll
;         for (int j = 0; j < 8; ++j) ss += (v[j][0] * v[j][0] + v[j][1] * v[j][1]) + (v[j][2] * v[j][2] + v[j][3] * v[j][3]);
;         const float r = rsqrtf(wave_sum(ss) * (1.f / D) + EPS);
;         u32x2* o8 = (u32x2*)(dst + (size_t)row * D) + X.lane;
; #pragma unroll
;         for (int j = 0; j < 8; ++j) {
;             const f32x4 y = (v[j] * r) * pa[j] + pb[j];
	v_lshlrev_b32_e32 v178, 16, v162
	v_and_b32_e32 v179, 0xffff0000, v162
	v_lshlrev_b32_e32 v180, 16, v163
	v_and_b32_e32 v181, 0xffff0000, v163
	v_pk_add_f32 v[130:131], v[130:131], v[178:179]
	v_pk_add_f32 v[132:133], v[132:133], v[180:181]
	v_pk_mul_f32 v[182:183], v[130:131], v[130:131]
	v_pk_mul_f32 v[184:185], v[132:133], v[132:133]
	v_lshlrev_b32_e32 v178, 16, v164
	v_and_b32_e32 v179, 0xffff0000, v164
	v_lshlrev_b32_e32 v180, 16, v165
	v_and_b32_e32 v181, 0xffff0000, v165
	v_pk_add_f32 v[134:135], v[134:135], v[178:179]
	v_pk_add_f32 v[136:137], v[136:137], v[180:181]
	v_pk_fma_f32 v[182:183], v[134:135], v[134:135], v[182:183]
	v_pk_fma_f32 v[184:185], v[136:137], v[136:137], v[184:185]
	v_lshlrev_b32_e32 v178, 16, v166
	v_and_b32_e32 v179, 0xffff0000, v166
	v_lshlrev_b32_e32 v180, 16, v167
	v_and_b32_e32 v181, 0xffff0000, v167
	v_pk_add_f32 v[138:139], v[138:139], v[178:179]
	v_pk_add_f32 v[140:141], v[140:141], v[180:181]
	v_pk_fma_f32 v[182:183], v[138:139], v[138:139], v[182:183]
	v_pk_fma_f32 v[184:185], v[140:141], v[140:141], v[184:185]
	v_lshlrev_b32_e32 v178, 16, v168
	v_and_b32_e32 v179, 0xffff0000, v168
	v_lshlrev_b32_e32 v180, 16, v169
	v_and_b32_e32 v181, 0xffff0000, v169
	v_pk_add_f32 v[142:143], v[142:143], v[178:179]
	v_pk_add_f32 v[144:145], v[144:145], v[180:181]
	v_pk_fma_f32 v[182:183], v[142:143], v[142:143], v[182:183]
	v_pk_fma_f32 v[184:185], v[144:145], v[144:145], v[184:185]
	v_lshlrev_b32_e32 v178, 16, v170
	v_and_b32_e32 v179, 0xffff0000, v170
	v_lshlrev_b32_e32 v180, 16, v171
	v_and_b32_e32 v181, 0xffff0000, v171
	v_pk_add_f32 v[146:147], v[146:147], v[178:179]
	v_pk_add_f32 v[148:149], v[148:149], v[180:181]
	v_pk_fma_f32 v[182:183], v[146:147], v[146:147], v[182:183]
	v_pk_fma_f32 v[184:185], v[148:149], v[148:149], v[184:185]
	v_lshlrev_b32_e32 v178, 16, v172
	v_and_b32_e32 v179, 0xffff0000, v172
	v_lshlrev_b32_e32 v180, 16, v173
	v_and_b32_e32 v181, 0xffff0000, v173
	v_pk_add_f32 v[150:151], v[150:151], v[178:179]
	v_pk_add_f32 v[152:153], v[152:153], v[180:181]
	v_pk_fma_f32 v[182:183], v[150:151], v[150:151], v[182:183]
	v_pk_fma_f32 v[184:185], v[152:153], v[152:153], v[184:185]
	v_lshlrev_b32_e32 v178, 16, v174
	v_and_b32_e32 v179, 0xffff0000, v174
	v_lshlrev_b32_e32 v180, 16, v175
	v_and_b32_e32 v181, 0xffff0000, v175
	v_pk_add_f32 v[154:155], v[154:155], v[178:179]
	v_pk_add_f32 v[156:157], v[156:157], v[180:181]
	v_pk_fma_f32 v[182:183], v[154:155], v[154:155], v[182:183]
	v_pk_fma_f32 v[184:185], v[156:157], v[156:157], v[184:185]
	v_lshlrev_b32_e32 v178, 16, v176
	v_and_b32_e32 v179, 0xffff0000, v176
	v_lshlrev_b32_e32 v180, 16, v177
	v_and_b32_e32 v181, 0xffff0000, v177
	v_pk_add_f32 v[158:159], v[158:159], v[178:179]
	v_pk_add_f32 v[160:161], v[160:161], v[180:181]
	v_pk_fma_f32 v[182:183], v[158:159], v[158:159], v[182:183]
	v_pk_fma_f32 v[184:185], v[160:161], v[160:161], v[184:185]
	v_pk_add_f32 v[182:183], v[182:183], v[184:185]
	s_nop 0
	v_add_f32_e32 v180, v182, v183
	ds_bpermute_b32 v178, v120, v180
	s_waitcnt lgkmcnt(0)
	v_add_f32_e32 v180, v180, v178
	ds_bpermute_b32 v178, v121, v180
	s_waitcnt lgkmcnt(0)
	v_add_f32_e32 v180, v180, v178
	ds_bpermute_b32 v178, v122, v180
	s_waitcnt lgkmcnt(0)
	v_add_f32_e32 v180, v180, v178
	ds_bpermute_b32 v178, v123, v180
	s_waitcnt lgkmcnt(0)
	v_add_f32_e32 v180, v180, v178
	ds_bpermute_b32 v178, v124, v180
	s_waitcnt lgkmcnt(0)
	v_add_f32_e32 v180, v180, v178
	ds_bpermute_b32 v178, v125, v180
	s_waitcnt lgkmcnt(0)
	v_add_f32_e32 v180, v180, v178
	v_fmamk_f32 v180, v180, 0x3a000000, v126
	v_mul_f32_e32 v178, 0x4b800000, v180
	v_cmp_gt_f32_e32 vcc, s2, v180
	s_nop 1
	v_cndmask_b32_e32 v180, v180, v178, vcc
	v_rsq_f32_e32 v180, v180
	s_nop 0
	v_mul_f32_e32 v178, 0x45800000, v180
	v_cndmask_b32_e32 v178, v180, v178, vcc
	v_pk_mul_f32 v[130:131], v[130:131], v[178:179] op_sel_hi:[1,0]
	v_pk_mul_f32 v[132:133], v[132:133], v[178:179] op_sel_hi:[1,0]
	v_pk_mul_f32 v[134:135], v[134:135], v[178:179] op_sel_hi:[1,0]
	v_pk_mul_f32 v[136:137], v[136:137], v[178:179] op_sel_hi:[1,0]
	v_pk_mul_f32 v[138:139], v[138:139], v[178:179] op_sel_hi:[1,0]
	v_pk_mul_f32 v[140:141], v[140:141], v[178:179] op_sel_hi:[1,0]
	v_pk_mul_f32 v[142:143], v[142:143], v[178:179] op_sel_hi:[1,0]
	v_pk_mul_f32 v[144:145], v[144:145], v[178:179] op_sel_hi:[1,0]
	v_pk_mul_f32 v[146:147], v[146:147], v[178:179] op_sel_hi:[1,0]
	v_pk_mul_f32 v[148:149], v[148:149], v[178:179] op_sel_hi:[1,0]
	v_pk_mul_f32 v[150:151], v[150:151], v[178:179] op_sel_hi:[1,0]
	v_pk_mul_f32 v[152:153], v[152:153], v[178:179] op_sel_hi:[1,0]
	v_pk_mul_f32 v[154:155], v[154:155], v[178:179] op_sel_hi:[1,0]
	v_pk_mul_f32 v[156:157], v[156:157], v[178:179] op_sel_hi:[1,0]
	v_pk_mul_f32 v[158:159], v[158:159], v[178:179] op_sel_hi:[1,0]
	v_pk_mul_f32 v[160:161], v[160:161], v[178:179] op_sel_hi:[1,0]
	v_pk_fma_f32 v[130:131], v[66:67], v[130:131], v[0:1]
	v_pk_fma_f32 v[132:133], v[64:65], v[132:133], v[2:3]
	v_pk_fma_f32 v[134:135], v[70:71], v[134:135], v[4:5]
	v_pk_fma_f32 v[136:137], v[68:69], v[136:137], v[6:7]
	v_pk_fma_f32 v[138:139], v[74:75], v[138:139], v[8:9]
	v_pk_fma_f32 v[140:141], v[72:73], v[140:141], v[10:11]
	v_pk_fma_f32 v[142:143], v[78:79], v[142:143], v[12:13]
	v_pk_fma_f32 v[144:145], v[76:77], v[144:145], v[14:15]
	v_pk_fma_f32 v[146:147], v[82:83], v[146:147], v[16:17]
	v_pk_fma_f32 v[148:149], v[80:81], v[148:149], v[18:19]
	v_pk_fma_f32 v[150:151], v[86:87], v[150:151], v[20:21]
	v_pk_fma_f32 v[152:153], v[84:85], v[152:153], v[22:23]
	v_pk_fma_f32 v[154:155], v[90:91], v[154:155], v[24:25]
	v_pk_fma_f32 v[156:157], v[88:89], v[156:157], v[26:27]
	v_pk_fma_f32 v[158:159], v[94:95], v[158:159], v[28:29]
; __device__ __forceinline__ unsigned pk2_rne(float lo, float hi) { const f32x2_t f = {lo, hi}; return __builtin_bit_cast(unsigned, __builtin_convertvector(f, bf16x2_t)); }
; __device__ __forceinline__ float bflo(unsigned w) { return __uint_as_float(w << 16); }
; __device__ __forceinline__ float bfhi(unsigned w) { return __uint_as_float(w & 0xffff0000u); }
; __device__ __forceinline__ void rows_norm_mod(Ctx& X, const float* src, const bf16_t* delta, float* x1out, const float* w, const float* sc, const float* sh, bf16_t* dst, bool do_cs) {
;     ...
;     for (int row = X.gw; row < S; row += X.NGW) {
;         const f32x4* xr = (const f32x4*)(src + (size_t)row * D) + X.lane;
;         f32x4 v[8]; float ss = 0.f;
; #pragma unroll
;         for (int j = 0; j < 8; ++j) v[j] = __builtin_nontemporal_load(xr + 64 * j);
;         if (delta) {
;             const u32x2* dr = (const u32x2*)(delta + (size_t)row * D) + X.lane;
; #pragma unroll
;             for (int j = 0; j < 8; ++j) { const u32x2 d2 = dr[64 * j]; v[j][0] += bflo(d2.x); v[j][1] += bfhi(d2.x); v[j][2] += bflo(d2.y); v[j][3] += bfhi(d2.y); }
;             if (x1out) {
;                 f32x4* xo = (f32x4*)(x1out + (size_t)row * D) + X.lane;
; #pragma unroll
;                 for (int j = 0; j < 8; ++j) xo[64 * j] = v[j];
;             }
;         }
; #pragma unroll
;         for (int j = 0; j < 8; ++j) ss += (v[j][0] * v[j][0] + v[j][1] * v[j][1]) + (v[j][2] * v[j][2] + v[j][3] * v[j][3]);
;         const float r = rsqrtf(wave_sum(ss) * (1.f / D) + EPS);
;         u32x2* o8 = (u32x2*)(dst + (size_t)row * D) + X.lane;
; #pragma unroll
;         for (int j = 0; j < 8; ++j) {
;             const f32x4 y = (v[j] * r) * pa[j] + pb[j];
;             u32x2 p; p.x = pk2_rne(y[0], y[1]); p.y = pk2_rne(y[2], y[3]); o8[64 * j] = p;
;         }
	v_pk_fma_f32 v[160:161], v[92:93], v[160:161], v[30:31]
	v_cvt_pk_bf16_f32 v130, v130, v131
	v_cvt_pk_bf16_f32 v131, v132, v133
	v_cvt_pk_bf16_f32 v134, v134, v135
	v_cvt_pk_bf16_f32 v135, v136, v137
	v_cvt_pk_bf16_f32 v138, v138, v139
	v_cvt_pk_bf16_f32 v139, v140, v141
	v_cvt_pk_bf16_f32 v142, v142, v143
	v_cvt_pk_bf16_f32 v143, v144, v145
	v_cvt_pk_bf16_f32 v146, v146, v147
	v_cvt_pk_bf16_f32 v147, v148, v149
	v_cvt_pk_bf16_f32 v150, v150, v151
	v_cvt_pk_bf16_f32 v151, v152, v153
	v_cvt_pk_bf16_f32 v154, v154, v155
	v_cvt_pk_bf16_f32 v155, v156, v157
	v_cvt_pk_bf16_f32 v158, v158, v159
	v_cvt_pk_bf16_f32 v159, v160, v161
	global_store_dwordx2 v188, v[130:131], s[14:15] offset:0
	global_store_dwordx2 v188, v[134:135], s[14:15] offset:512
	global_store_dwordx2 v188, v[138:139], s[14:15] offset:1024
	global_store_dwordx2 v188, v[142:143], s[14:15] offset:1536
	global_store_dwordx2 v188, v[146:147], s[14:15] offset:2048
	global_store_dwordx2 v188, v[150:151], s[14:15] offset:2560
	global_store_dwordx2 v188, v[154:155], s[14:15] offset:3072
	global_store_dwordx2 v188, v[158:159], s[14:15] offset:3584
	s_add_u32 s14, s14, s6
	s_addc_u32 s15, s15, s7
	global_load_dwordx2 v[162:163], v188, s[12:13] offset:0
	global_load_dwordx2 v[164:165], v188, s[12:13] offset:512
	global_load_dwordx2 v[166:167], v188, s[12:13] offset:1024
	global_load_dwordx2 v[168:169], v188, s[12:13] offset:1536
	global_load_dwordx2 v[170:171], v188, s[12:13] offset:2048
	global_load_dwordx2 v[172:173], v188, s[12:13] offset:2560
	global_load_dwordx2 v[174:175], v188, s[12:13] offset:3072
	global_load_dwordx2 v[176:177], v188, s[12:13] offset:3584
	global_load_dwordx4 v[130:133], v186, s[10:11] offset:0 nt
	global_load_dwordx4 v[134:137], v186, s[10:11] offset:1024 nt
	global_load_dwordx4 v[138:141], v186, s[10:11] offset:2048 nt
	global_load_dwordx4 v[142:145], v186, s[10:11] offset:3072 nt
	global_load_dwordx4 v[146:149], v187, s[10:11] offset:0 nt
	global_load_dwordx4 v[150:153], v187, s[10:11] offset:1024 nt
	global_load_dwordx4 v[154:157], v187, s[10:11] offset:2048 nt
	global_load_dwordx4 v[158:161], v187, s[10:11] offset:3072 nt
	s_add_u32 s10, s10, s4
	s_addc_u32 s11, s11, s5
	s_add_u32 s12, s12, s6
	s_addc_u32 s13, s13, s7
	s_waitcnt vmcnt(24)
	v_lshlrev_b32_e32 v178, 16, v100
	v_and_b32_e32 v179, 0xffff0000, v100
	v_lshlrev_b32_e32 v180, 16, v101
	v_and_b32_e32 v181, 0xffff0000, v101
	v_pk_add_f32 v[32:33], v[32:33], v[178:179]
	v_pk_add_f32 v[34:35], v[34:35], v[180:181]
	v_pk_mul_f32 v[182:183], v[32:33], v[32:33]
	v_pk_mul_f32 v[184:185], v[34:35], v[34:35]
	v_lshlrev_b32_e32 v178, 16, v102
	v_and_b32_e32 v179, 0xffff0000, v102
	v_lshlrev_b32_e32 v180, 16, v103
	v_and_b32_e32 v181, 0xffff0000, v103
	v_pk_add_f32 v[36:37], v[36:37], v[178:179]
	v_pk_add_f32 v[38:39], v[38:39], v[180:181]
	v_pk_fma_f32 v[182:183], v[36:37], v[36:37], v[182:183]
	v_pk_fma_f32 v[184:185], v[38:39], v[38:39], v[184:185]
	v_lshlrev_b32_e32 v178, 16, v104
	v_and_b32_e32 v179, 0xffff0000, v104
	v_lshlrev_b32_e32 v180, 16, v105
	v_and_b32_e32 v181, 0xffff0000, v105
	v_pk_add_f32 v[40:41], v[40:41], v[178:179]
	v_pk_add_f32 v[42:43], v[42:43], v[180:181]
	v_pk_fma_f32 v[182:183], v[40:41], v[40:41], v[182:183]
	v_pk_fma_f32 v[184:185], v[42:43], v[42:43], v[184:185]
	v_lshlrev_b32_e32 v178, 16, v106
	v_and_b32_e32 v179, 0xffff0000, v106
	v_lshlrev_b32_e32 v180, 16, v107
	v_and_b32_e32 v181, 0xffff0000, v107
	v_pk_add_f32 v[44:45], v[44:45], v[178:179]
	v_pk_add_f32 v[46:47], v[46:47], v[180:181]
	v_pk_fma_f32 v[182:183], v[44:45], v[44:45], v[182:183]
	v_pk_fma_f32 v[184:185], v[46:47], v[46:47], v[184:185]
	v_lshlrev_b32_e32 v178, 16, v108
	v_and_b32_e32 v179, 0xffff0000, v108
	v_lshlrev_b32_e32 v180, 16, v109
	v_and_b32_e32 v181, 0xffff0000, v109
	v_pk_add_f32 v[48:49], v[48:49], v[178:179]
	v_pk_add_f32 v[50:51], v[50:51], v[180:181]
	v_pk_fma_f32 v[182:183], v[48:49], v[48:49], v[182:183]
	v_pk_fma_f32 v[184:185], v[50:51], v[50:51], v[184:185]
	v_lshlrev_b32_e32 v178, 16, v110
	v_and_b32_e32 v179, 0xffff0000, v110
	v_lshlrev_b32_e32 v180, 16, v111
	v_and_b32_e32 v181, 0xffff0000, v111
	v_pk_add_f32 v[52:53], v[52:53], v[178:179]
	v_pk_add_f32 v[54:55], v[54:55], v[180:181]
	v_pk_fma_f32 v[182:183], v[52:53], v[52:53], v[182:183]
	v_pk_fma_f32 v[184:185], v[54:55], v[54:55], v[184:185]
	v_lshlrev_b32_e32 v178, 16, v112
	v_and_b32_e32 v179, 0xffff0000, v112
	v_lshlrev_b32_e32 v180, 16, v113
	v_and_b32_e32 v181, 0xffff0000, v113
	v_pk_add_f32 v[56:57], v[56:57], v[178:179]
	v_pk_add_f32 v[58:59], v[58:59], v[180:181]
	v_pk_fma_f32 v[182:183], v[56:57], v[56:57], v[182:183]
	v_pk_fma_f32 v[184:185], v[58:59], v[58:59], v[184:185]
	v_lshlrev_b32_e32 v178, 16, v114
	v_and_b32_e32 v179, 0xffff0000, v114
	v_lshlrev_b32_e32 v180, 16, v115
	v_and_b32_e32 v181, 0xffff0000, v115
	v_pk_add_f32 v[60:61], v[60:61], v[178:179]
	v_pk_add_f32 v[62:63], v[62:63], v[180:181]
	v_pk_fma_f32 v[182:183], v[60:61], v[60:61], v[182:183]
	v_pk_fma_f32 v[184:185], v[62:63], v[62:63], v[184:185]
	v_pk_add_f32 v[182:183], v[182:183], v[184:185]
	s_nop 0
	v_add_f32_e32 v180, v182, v183
	ds_bpermute_b32 v178, v120, v180
	s_waitcnt lgkmcnt(0)
	v_add_f32_e32 v180, v180, v178
	ds_bpermute_b32 v178, v121, v180
	s_waitcnt lgkmcnt(0)
	v_add_f32_e32 v180, v180, v178
	ds_bpermute_b32 v178, v122, v180
	s_waitcnt lgkmcnt(0)
	v_add_f32_e32 v180, v180, v178
	ds_bpermute_b32 v178, v123, v180
	s_waitcnt lgkmcnt(0)
	v_add_f32_e32 v180, v180, v178
	ds_bpermute_b32 v178, v124, v180
	s_waitcnt lgkmcnt(0)
	v_add_f32_e32 v180, v180, v178
	ds_bpermute_b32 v178, v125, v180
	s_waitcnt lgkmcnt(0)
; __device__ __forceinline__ unsigned pk2_rne(float lo, float hi) { const f32x2_t f = {lo, hi}; return __builtin_bit_cast(unsigned, __builtin_convertvector(f, bf16x2_t)); }
; __device__ __forceinline__ float bflo(unsigned w) { return __uint_as_float(w << 16); }
; __device__ __forceinline__ float bfhi(unsigned w) { return __uint_as_float(w & 0xffff0000u); }
; __device__ __forceinline__ void rows_norm_mod(Ctx& X, const float* src, const bf16_t* delta, float* x1out, const float* w, const float* sc, const float* sh, bf16_t* dst, bool do_cs) {
;     ...
;         const f32x4* xr = (const f32x4*)(src + (size_t)row * D) + X.lane;
;         f32x4 v[8]; float ss = 0.f;
; #pragma unroll
;         for (int j = 0; j < 8; ++j) v[j] = __builtin_nontemporal_load(xr + 64 * j);
;         if (delta) {
;             const u32x2* dr = (const u32x2*)(delta + (size_t)row * D) + X.lane;
; #pragma unroll
;             for (int j = 0; j < 8; ++j) { const u32x2 d2 = dr[64 * j]; v[j][0] += bflo(d2.x); v[j][1] += bfhi(d2.x); v[j][2] += bflo(d2.y); v[j][3] += bfhi(d2.y); }
;     ...
;         const float r = rsqrtf(wave_sum(ss) * (1.f / D) + EPS);
;         u32x2* o8 = (u32x2*)(dst + (size_t)row * D) + X.lane;
; #pragma unroll
;         for (int j = 0; j < 8; ++j) {
;             const f32x4 y = (v[j] * r) * pa[j] + pb[j];
;             u32x2 p; p.x = pk2_rne(y[0], y[1]); p.y = pk2_rne(y[2], y[3]); o8[64 * j] = p;
;         }
	v_add_f32_e32 v180, v180, v178
	v_fmamk_f32 v180, v180, 0x3a000000, v126
	v_mul_f32_e32 v178, 0x4b800000, v180
	v_cmp_gt_f32_e32 vcc, s2, v180
	s_nop 1
	v_cndmask_b32_e32 v180, v180, v178, vcc
	v_rsq_f32_e32 v180, v180
	s_nop 0
	v_mul_f32_e32 v178, 0x45800000, v180
	v_cndmask_b32_e32 v178, v180, v178, vcc
	v_pk_mul_f32 v[32:33], v[32:33], v[178:179] op_sel_hi:[1,0]
	v_pk_mul_f32 v[34:35], v[34:35], v[178:179] op_sel_hi:[1,0]
	v_pk_mul_f32 v[36:37], v[36:37], v[178:179] op_sel_hi:[1,0]
	v_pk_mul_f32 v[38:39], v[38:39], v[178:179] op_sel_hi:[1,0]
	v_pk_mul_f32 v[40:41], v[40:41], v[178:179] op_sel_hi:[1,0]
	v_pk_mul_f32 v[42:43], v[42:43], v[178:179] op_sel_hi:[1,0]
	v_pk_mul_f32 v[44:45], v[44:45], v[178:179] op_sel_hi:[1,0]
	v_pk_mul_f32 v[46:47], v[46:47], v[178:179] op_sel_hi:[1,0]
	v_pk_mul_f32 v[48:49], v[48:49], v[178:179] op_sel_hi:[1,0]
	v_pk_mul_f32 v[50:51], v[50:51], v[178:179] op_sel_hi:[1,0]
	v_pk_mul_f32 v[52:53], v[52:53], v[178:179] op_sel_hi:[1,0]
	v_pk_mul_f32 v[54:55], v[54:55], v[178:179] op_sel_hi:[1,0]
	v_pk_mul_f32 v[56:57], v[56:57], v[178:179] op_sel_hi:[1,0]
	v_pk_mul_f32 v[58:59], v[58:59], v[178:179] op_sel_hi:[1,0]
	v_pk_mul_f32 v[60:61], v[60:61], v[178:179] op_sel_hi:[1,0]
	v_pk_mul_f32 v[62:63], v[62:63], v[178:179] op_sel_hi:[1,0]
	v_pk_fma_f32 v[32:33], v[66:67], v[32:33], v[0:1]
	v_pk_fma_f32 v[34:35], v[64:65], v[34:35], v[2:3]
	v_pk_fma_f32 v[36:37], v[70:71], v[36:37], v[4:5]
	v_pk_fma_f32 v[38:39], v[68:69], v[38:39], v[6:7]
	v_pk_fma_f32 v[40:41], v[74:75], v[40:41], v[8:9]
	v_pk_fma_f32 v[42:43], v[72:73], v[42:43], v[10:11]
	v_pk_fma_f32 v[44:45], v[78:79], v[44:45], v[12:13]
	v_pk_fma_f32 v[46:47], v[76:77], v[46:47], v[14:15]
	v_pk_fma_f32 v[48:49], v[82:83], v[48:49], v[16:17]
	v_pk_fma_f32 v[50:51], v[80:81], v[50:51], v[18:19]
	v_pk_fma_f32 v[52:53], v[86:87], v[52:53], v[20:21]
	v_pk_fma_f32 v[54:55], v[84:85], v[54:55], v[22:23]
	v_pk_fma_f32 v[56:57], v[90:91], v[56:57], v[24:25]
	v_pk_fma_f32 v[58:59], v[88:89], v[58:59], v[26:27]
	v_pk_fma_f32 v[60:61], v[94:95], v[60:61], v[28:29]
	v_pk_fma_f32 v[62:63], v[92:93], v[62:63], v[30:31]
	v_cvt_pk_bf16_f32 v32, v32, v33
	v_cvt_pk_bf16_f32 v33, v34, v35
	v_cvt_pk_bf16_f32 v36, v36, v37
	v_cvt_pk_bf16_f32 v37, v38, v39
	v_cvt_pk_bf16_f32 v40, v40, v41
	v_cvt_pk_bf16_f32 v41, v42, v43
	v_cvt_pk_bf16_f32 v44, v44, v45
	v_cvt_pk_bf16_f32 v45, v46, v47
	v_cvt_pk_bf16_f32 v48, v48, v49
	v_cvt_pk_bf16_f32 v49, v50, v51
	v_cvt_pk_bf16_f32 v52, v52, v53
	v_cvt_pk_bf16_f32 v53, v54, v55
	v_cvt_pk_bf16_f32 v56, v56, v57
	v_cvt_pk_bf16_f32 v57, v58, v59
	v_cvt_pk_bf16_f32 v60, v60, v61
	v_cvt_pk_bf16_f32 v61, v62, v63
	global_store_dwordx2 v188, v[32:33], s[14:15] offset:0
	global_store_dwordx2 v188, v[36:37], s[14:15] offset:512
	global_store_dwordx2 v188, v[40:41], s[14:15] offset:1024
	global_store_dwordx2 v188, v[44:45], s[14:15] offset:1536
	global_store_dwordx2 v188, v[48:49], s[14:15] offset:2048
	global_store_dwordx2 v188, v[52:53], s[14:15] offset:2560
	global_store_dwordx2 v188, v[56:57], s[14:15] offset:3072
	global_store_dwordx2 v188, v[60:61], s[14:15] offset:3584
	s_add_u32 s14, s14, s6
	s_addc_u32 s15, s15, s7
	global_load_dwordx2 v[100:101], v188, s[12:13] offset:0
	global_load_dwordx2 v[102:103], v188, s[12:13] offset:512
	global_load_dwordx2 v[104:105], v188, s[12:13] offset:1024
	global_load_dwordx2 v[106:107], v188, s[12:13] offset:1536
	global_load_dwordx2 v[108:109], v188, s[12:13] offset:2048
	global_load_dwordx2 v[110:111], v188, s[12:13] offset:2560
	global_load_dwordx2 v[112:113], v188, s[12:13] offset:3072
	global_load_dwordx2 v[114:115], v188, s[12:13] offset:3584
	global_load_dwordx4 v[32:35], v186, s[10:11] offset:0 nt
	global_load_dwordx4 v[36:39], v186, s[10:11] offset:1024 nt
	global_load_dwordx4 v[40:43], v186, s[10:11] offset:2048 nt
	global_load_dwordx4 v[44:47], v186, s[10:11] offset:3072 nt
	global_load_dwordx4 v[48:51], v187, s[10:11] offset:0 nt
	global_load_dwordx4 v[52:55], v187, s[10:11] offset:1024 nt
	global_load_dwordx4 v[56:59], v187, s[10:11] offset:2048 nt
	global_load_dwordx4 v[60:63], v187, s[10:11] offset:3072 nt
	s_add_u32 s10, s10, s4
	s_addc_u32 s11, s11, s5
	s_add_u32 s12, s12, s6
	s_addc_u32 s13, s13, s7
	s_waitcnt vmcnt(24)
; __device__ __forceinline__ float bflo(unsigned w) { return __uint_as_float(w << 16); }
; __device__ __forceinline__ float bfhi(unsigned w) { return __uint_as_float(w & 0xffff0000u); }
; __device__ __forceinline__ void rows_norm_mod(Ctx& X, const float* src, const bf16_t* delta, float* x1out, const float* w, const float* sc, const float* sh, bf16_t* dst, bool do_cs) {
;     ...
;             for (int j = 0; j < 8; ++j) { const u32x2 d2 = dr[64 * j]; v[j][0] += bflo(d2.x); v[j][1] += bfhi(d2.x); v[j][2] += bflo(d2.y); v[j][3] += bfhi(d2.y); }
;             if (x1out) {
;                 f32x4* xo = (f32x4*)(x1out + (size_t)row * D) + X.lane;
; #pragma unroll
;                 for (int j = 0; j < 8; ++j) xo[64 * j] = v[j];
;             }
;         }
; #pragma unroll
;         for (int j = 0; j < 8; ++j) ss += (v[j][0] * v[j][0] + v[j][1] * v[j][1]) + (v[j][2] * v[j][2] + v[j][3] * v[j][3]);
;         const float r = rsqrtf(wave_sum(ss) * (1.f / D) + EPS);
;         u32x2* o8 = (u32x2*)(dst + (size_t)row * D) + X.lane;
; #pragma unroll
;         for (int j = 0; j < 8; ++j) {
;             const f32x4 y = (v[j] * r) * pa[j] + pb[j];
	v_lshlrev_b32_e32 v178, 16, v162
	v_and_b32_e32 v179, 0xffff0000, v162
	v_lshlrev_b32_e32 v180, 16, v163
	v_and_b32_e32 v181, 0xffff0000, v163
	v_pk_add_f32 v[130:131], v[130:131], v[178:179]
	v_pk_add_f32 v[132:133], v[132:133], v[180:181]
	v_pk_mul_f32 v[182:183], v[130:131], v[130:131]
	v_pk_mul_f32 v[184:185], v[132:133], v[132:133]
	v_lshlrev_b32_e32 v178, 16, v164
	v_and_b32_e32 v179, 0xffff0000, v164
	v_lshlrev_b32_e32 v180, 16, v165
	v_and_b32_e32 v181, 0xffff0000, v165
	v_pk_add_f32 v[134:135], v[134:135], v[178:179]
	v_pk_add_f32 v[136:137], v[136:137], v[180:181]
	v_pk_fma_f32 v[182:183], v[134:135], v[134:135], v[182:183]
	v_pk_fma_f32 v[184:185], v[136:137], v[136:137], v[184:185]
	v_lshlrev_b32_e32 v178, 16, v166
	v_and_b32_e32 v179, 0xffff0000, v166
	v_lshlrev_b32_e32 v180, 16, v167
	v_and_b32_e32 v181, 0xffff0000, v167
	v_pk_add_f32 v[138:139], v[138:139], v[178:179]
	v_pk_add_f32 v[140:141], v[140:141], v[180:181]
	v_pk_fma_f32 v[182:183], v[138:139], v[138:139], v[182:183]
	v_pk_fma_f32 v[184:185], v[140:141], v[140:141], v[184:185]
	v_lshlrev_b32_e32 v178, 16, v168
	v_and_b32_e32 v179, 0xffff0000, v168
	v_lshlrev_b32_e32 v180, 16, v169
	v_and_b32_e32 v181, 0xffff0000, v169
	v_pk_add_f32 v[142:143], v[142:143], v[178:179]
	v_pk_add_f32 v[144:145], v[144:145], v[180:181]
	v_pk_fma_f32 v[182:183], v[142:143], v[142:143], v[182:183]
	v_pk_fma_f32 v[184:185], v[144:145], v[144:145], v[184:185]
	v_lshlrev_b32_e32 v178, 16, v170
	v_and_b32_e32 v179, 0xffff0000, v170
	v_lshlrev_b32_e32 v180, 16, v171
	v_and_b32_e32 v181, 0xffff0000, v171
	v_pk_add_f32 v[146:147], v[146:147], v[178:179]
	v_pk_add_f32 v[148:149], v[148:149], v[180:181]
	v_pk_fma_f32 v[182:183], v[146:147], v[146:147], v[182:183]
	v_pk_fma_f32 v[184:185], v[148:149], v[148:149], v[184:185]
	v_lshlrev_b32_e32 v178, 16, v172
	v_and_b32_e32 v179, 0xffff0000, v172
	v_lshlrev_b32_e32 v180, 16, v173
	v_and_b32_e32 v181, 0xffff0000, v173
	v_pk_add_f32 v[150:151], v[150:151], v[178:179]
	v_pk_add_f32 v[152:153], v[152:153], v[180:181]
	v_pk_fma_f32 v[182:183], v[150:151], v[150:151], v[182:183]
	v_pk_fma_f32 v[184:185], v[152:153], v[152:153], v[184:185]
	v_lshlrev_b32_e32 v178, 16, v174
	v_and_b32_e32 v179, 0xffff0000, v174
	v_lshlrev_b32_e32 v180, 16, v175
	v_and_b32_e32 v181, 0xffff0000, v175
	v_pk_add_f32 v[154:155], v[154:155], v[178:179]
	v_pk_add_f32 v[156:157], v[156:157], v[180:181]
	v_pk_fma_f32 v[182:183], v[154:155], v[154:155], v[182:183]
	v_pk_fma_f32 v[184:185], v[156:157], v[156:157], v[184:185]
	v_lshlrev_b32_e32 v178, 16, v176
	v_and_b32_e32 v179, 0xffff0000, v176
	v_lshlrev_b32_e32 v180, 16, v177
	v_and_b32_e32 v181, 0xffff0000, v177
	v_pk_add_f32 v[158:159], v[158:159], v[178:179]
	v_pk_add_f32 v[160:161], v[160:161], v[180:181]
	v_pk_fma_f32 v[182:183], v[158:159], v[158:159], v[182:183]
	v_pk_fma_f32 v[184:185], v[160:161], v[160:161], v[184:185]
	v_pk_add_f32 v[182:183], v[182:183], v[184:185]
	s_nop 0
	v_add_f32_e32 v180, v182, v183
	ds_bpermute_b32 v178, v120, v180
	s_waitcnt lgkmcnt(0)
	v_add_f32_e32 v180, v180, v178
	ds_bpermute_b32 v178, v121, v180
	s_waitcnt lgkmcnt(0)
	v_add_f32_e32 v180, v180, v178
	ds_bpermute_b32 v178, v122, v180
	s_waitcnt lgkmcnt(0)
	v_add_f32_e32 v180, v180, v178
	ds_bpermute_b32 v178, v123, v180
	s_waitcnt lgkmcnt(0)
	v_add_f32_e32 v180, v180, v178
	ds_bpermute_b32 v178, v124, v180
	s_waitcnt lgkmcnt(0)
	v_add_f32_e32 v180, v180, v178
	ds_bpermute_b32 v178, v125, v180
	s_waitcnt lgkmcnt(0)
	v_add_f32_e32 v180, v180, v178
	v_fmamk_f32 v180, v180, 0x3a000000, v126
	v_mul_f32_e32 v178, 0x4b800000, v180
	v_cmp_gt_f32_e32 vcc, s2, v180
	s_nop 1
	v_cndmask_b32_e32 v180, v180, v178, vcc
	v_rsq_f32_e32 v180, v180
	s_nop 0
	v_mul_f32_e32 v178, 0x45800000, v180
	v_cndmask_b32_e32 v178, v180, v178, vcc
	v_pk_mul_f32 v[130:131], v[130:131], v[178:179] op_sel_hi:[1,0]
	v_pk_mul_f32 v[132:133], v[132:133], v[178:179] op_sel_hi:[1,0]
	v_pk_mul_f32 v[134:135], v[134:135], v[178:179] op_sel_hi:[1,0]
	v_pk_mul_f32 v[136:137], v[136:137], v[178:179] op_sel_hi:[1,0]
	v_pk_mul_f32 v[138:139], v[138:139], v[178:179] op_sel_hi:[1,0]
	v_pk_mul_f32 v[140:141], v[140:141], v[178:179] op_sel_hi:[1,0]
	v_pk_mul_f32 v[142:143], v[142:143], v[178:179] op_sel_hi:[1,0]
	v_pk_mul_f32 v[144:145], v[144:145], v[178:179] op_sel_hi:[1,0]
	v_pk_mul_f32 v[146:147], v[146:147], v[178:179] op_sel_hi:[1,0]
	v_pk_mul_f32 v[148:149], v[148:149], v[178:179] op_sel_hi:[1,0]
	v_pk_mul_f32 v[150:151], v[150:151], v[178:179] op_sel_hi:[1,0]
	v_pk_mul_f32 v[152:153], v[152:153], v[178:179] op_sel_hi:[1,0]
	v_pk_mul_f32 v[154:155], v[154:155], v[178:179] op_sel_hi:[1,0]
	v_pk_mul_f32 v[156:157], v[156:157], v[178:179] op_sel_hi:[1,0]
	v_pk_mul_f32 v[158:159], v[158:159], v[178:179] op_sel_hi:[1,0]
	v_pk_mul_f32 v[160:161], v[160:161], v[178:179] op_sel_hi:[1,0]
	v_pk_fma_f32 v[130:131], v[66:67], v[130:131], v[0:1]
	v_pk_fma_f32 v[132:133], v[64:65], v[132:133], v[2:3]
	v_pk_fma_f32 v[134:135], v[70:71], v[134:135], v[4:5]
	v_pk_fma_f32 v[136:137], v[68:69], v[136:137], v[6:7]
	v_pk_fma_f32 v[138:139], v[74:75], v[138:139], v[8:9]
	v_pk_fma_f32 v[140:141], v[72:73], v[140:141], v[10:11]
	v_pk_fma_f32 v[142:143], v[78:79], v[142:143], v[12:13]
	v_pk_fma_f32 v[144:145], v[76:77], v[144:145], v[14:15]
	v_pk_fma_f32 v[146:147], v[82:83], v[146:147], v[16:17]
	v_pk_fma_f32 v[148:149], v[80:81], v[148:149], v[18:19]
	v_pk_fma_f32 v[150:151], v[86:87], v[150:151], v[20:21]
	v_pk_fma_f32 v[152:153], v[84:85], v[152:153], v[22:23]
	v_pk_fma_f32 v[154:155], v[90:91], v[154:155], v[24:25]
	v_pk_fma_f32 v[156:157], v[88:89], v[156:157], v[26:27]
	v_pk_fma_f32 v[158:159], v[94:95], v[158:159], v[28:29]
; __device__ __forceinline__ unsigned pk2_rne(float lo, float hi) { const f32x2_t f = {lo, hi}; return __builtin_bit_cast(unsigned, __builtin_convertvector(f, bf16x2_t)); }
; __device__ __forceinline__ float bflo(unsigned w) { return __uint_as_float(w << 16); }
; __device__ __forceinline__ float bfhi(unsigned w) { return __uint_as_float(w & 0xffff0000u); }
; __device__ __forceinline__ void rows_norm_mod(Ctx& X, const float* src, const bf16_t* delta, float* x1out, const float* w, const float* sc, const float* sh, bf16_t* dst, bool do_cs) {
;     ...
;     for (int row = X.gw; row < S; row += X.NGW) {
;         const f32x4* xr = (const f32x4*)(src + (size_t)row * D) + X.lane;
;         f32x4 v[8]; float ss = 0.f;
; #pragma unroll
;         for (int j = 0; j < 8; ++j) v[j] = __builtin_nontemporal_load(xr + 64 * j);
;         if (delta) {
;             const u32x2* dr = (const u32x2*)(delta + (size_t)row * D) + X.lane;
; #pragma unroll
;             for (int j = 0; j < 8; ++j) { const u32x2 d2 = dr[64 * j]; v[j][0] += bflo(d2.x); v[j][1] += bfhi(d2.x); v[j][2] += bflo(d2.y); v[j][3] += bfhi(d2.y); }
;             if (x1out) {
;                 f32x4* xo = (f32x4*)(x1out + (size_t)row * D) + X.lane;
; #pragma unroll
;                 for (int j = 0; j < 8; ++j) xo[64 * j] = v[j];
;             }
;         }
; #pragma unroll
;         for (int j = 0; j < 8; ++j) ss += (v[j][0] * v[j][0] + v[j][1] * v[j][1]) + (v[j][2] * v[j][2] + v[j][3] * v[j][3]);
;         const float r = rsqrtf(wave_sum(ss) * (1.f / D) + EPS);
;         u32x2* o8 = (u32x2*)(dst + (size_t)row * D) + X.lane;
; #pragma unroll
;         for (int j = 0; j < 8; ++j) {
;             const f32x4 y = (v[j] * r) * pa[j] + pb[j];
;             u32x2 p; p.x = pk2_rne(y[0], y[1]); p.y = pk2_rne(y[2], y[3]); o8[64 * j] = p;
;         }
	v_pk_fma_f32 v[160:161], v[92:93], v[160:161], v[30:31]
	v_cvt_pk_bf16_f32 v130, v130, v131
	v_cvt_pk_bf16_f32 v131, v132, v133
	v_cvt_pk_bf16_f32 v134, v134, v135
	v_cvt_pk_bf16_f32 v135, v136, v137
	v_cvt_pk_bf16_f32 v138, v138, v139
	v_cvt_pk_bf16_f32 v139, v140, v141
	v_cvt_pk_bf16_f32 v142, v142, v143
	v_cvt_pk_bf16_f32 v143, v144, v145
	v_cvt_pk_bf16_f32 v146, v146, v147
	v_cvt_pk_bf16_f32 v147, v148, v149
	v_cvt_pk_bf16_f32 v150, v150, v151
	v_cvt_pk_bf16_f32 v151, v152, v153
	v_cvt_pk_bf16_f32 v154, v154, v155
	v_cvt_pk_bf16_f32 v155, v156, v157
	v_cvt_pk_bf16_f32 v158, v158, v159
	v_cvt_pk_bf16_f32 v159, v160, v161
	global_store_dwordx2 v188, v[130:131], s[14:15] offset:0
	global_store_dwordx2 v188, v[134:135], s[14:15] offset:512
	global_store_dwordx2 v188, v[138:139], s[14:15] offset:1024
	global_store_dwordx2 v188, v[142:143], s[14:15] offset:1536
	global_store_dwordx2 v188, v[146:147], s[14:15] offset:2048
	global_store_dwordx2 v188, v[150:151], s[14:15] offset:2560
	global_store_dwordx2 v188, v[154:155], s[14:15] offset:3072
	global_store_dwordx2 v188, v[158:159], s[14:15] offset:3584
	s_add_u32 s14, s14, s6
	s_addc_u32 s15, s15, s7
	global_load_dwordx2 v[162:163], v188, s[12:13] offset:0
	global_load_dwordx2 v[164:165], v188, s[12:13] offset:512
	global_load_dwordx2 v[166:167], v188, s[12:13] offset:1024
	global_load_dwordx2 v[168:169], v188, s[12:13] offset:1536
	global_load_dwordx2 v[170:171], v188, s[12:13] offset:2048
	global_load_dwordx2 v[172:173], v188, s[12:13] offset:2560
	global_load_dwordx2 v[174:175], v188, s[12:13] offset:3072
	global_load_dwordx2 v[176:177], v188, s[12:13] offset:3584
	global_load_dwordx4 v[130:133], v186, s[10:11] offset:0 nt
	global_load_dwordx4 v[134:137], v186, s[10:11] offset:1024 nt
	global_load_dwordx4 v[138:141], v186, s[10:11] offset:2048 nt
	global_load_dwordx4 v[142:145], v186, s[10:11] offset:3072 nt
	global_load_dwordx4 v[146:149], v187, s[10:11] offset:0 nt
	global_load_dwordx4 v[150:153], v187, s[10:11] offset:1024 nt
	global_load_dwordx4 v[154:157], v187, s[10:11] offset:2048 nt
	global_load_dwordx4 v[158:161], v187, s[10:11] offset:3072 nt
	s_add_u32 s10, s10, s4
	s_addc_u32 s11, s11, s5
	s_add_u32 s12, s12, s6
	s_addc_u32 s13, s13, s7
	s_waitcnt vmcnt(24)
	v_lshlrev_b32_e32 v178, 16, v100
	v_and_b32_e32 v179, 0xffff0000, v100
	v_lshlrev_b32_e32 v180, 16, v101
	v_and_b32_e32 v181, 0xffff0000, v101
	v_pk_add_f32 v[32:33], v[32:33], v[178:179]
	v_pk_add_f32 v[34:35], v[34:35], v[180:181]
	v_pk_mul_f32 v[182:183], v[32:33], v[32:33]
	v_pk_mul_f32 v[184:185], v[34:35], v[34:35]
	v_lshlrev_b32_e32 v178, 16, v102
	v_and_b32_e32 v179, 0xffff0000, v102
	v_lshlrev_b32_e32 v180, 16, v103
	v_and_b32_e32 v181, 0xffff0000, v103
	v_pk_add_f32 v[36:37], v[36:37], v[178:179]
	v_pk_add_f32 v[38:39], v[38:39], v[180:181]
	v_pk_fma_f32 v[182:183], v[36:37], v[36:37], v[182:183]
	v_pk_fma_f32 v[184:185], v[38:39], v[38:39], v[184:185]
	v_lshlrev_b32_e32 v178, 16, v104
	v_and_b32_e32 v179, 0xffff0000, v104
	v_lshlrev_b32_e32 v180, 16, v105
	v_and_b32_e32 v181, 0xffff0000, v105
	v_pk_add_f32 v[40:41], v[40:41], v[178:179]
	v_pk_add_f32 v[42:43], v[42:43], v[180:181]
	v_pk_fma_f32 v[182:183], v[40:41], v[40:41], v[182:183]
	v_pk_fma_f32 v[184:185], v[42:43], v[42:43], v[184:185]
	v_lshlrev_b32_e32 v178, 16, v106
	v_and_b32_e32 v179, 0xffff0000, v106
	v_lshlrev_b32_e32 v180, 16, v107
	v_and_b32_e32 v181, 0xffff0000, v107
	v_pk_add_f32 v[44:45], v[44:45], v[178:179]
	v_pk_add_f32 v[46:47], v[46:47], v[180:181]
	v_pk_fma_f32 v[182:183], v[44:45], v[44:45], v[182:183]
	v_pk_fma_f32 v[184:185], v[46:47], v[46:47], v[184:185]
	v_lshlrev_b32_e32 v178, 16, v108
	v_and_b32_e32 v179, 0xffff0000, v108
	v_lshlrev_b32_e32 v180, 16, v109
	v_and_b32_e32 v181, 0xffff0000, v109
	v_pk_add_f32 v[48:49], v[48:49], v[178:179]
	v_pk_add_f32 v[50:51], v[50:51], v[180:181]
	v_pk_fma_f32 v[182:183], v[48:49], v[48:49], v[182:183]
	v_pk_fma_f32 v[184:185], v[50:51], v[50:51], v[184:185]
	v_lshlrev_b32_e32 v178, 16, v110
	v_and_b32_e32 v179, 0xffff0000, v110
	v_lshlrev_b32_e32 v180, 16, v111
	v_and_b32_e32 v181, 0xffff0000, v111
	v_pk_add_f32 v[52:53], v[52:53], v[178:179]
	v_pk_add_f32 v[54:55], v[54:55], v[180:181]
	v_pk_fma_f32 v[182:183], v[52:53], v[52:53], v[182:183]
	v_pk_fma_f32 v[184:185], v[54:55], v[54:55], v[184:185]
	v_lshlrev_b32_e32 v178, 16, v112
	v_and_b32_e32 v179, 0xffff0000, v112
	v_lshlrev_b32_e32 v180, 16, v113
	v_and_b32_e32 v181, 0xffff0000, v113
	v_pk_add_f32 v[56:57], v[56:57], v[178:179]
	v_pk_add_f32 v[58:59], v[58:59], v[180:181]
	v_pk_fma_f32 v[182:183], v[56:57], v[56:57], v[182:183]
	v_pk_fma_f32 v[184:185], v[58:59], v[58:59], v[184:185]
	v_lshlrev_b32_e32 v178, 16, v114
	v_and_b32_e32 v179, 0xffff0000, v114
	v_lshlrev_b32_e32 v180, 16, v115
	v_and_b32_e32 v181, 0xffff0000, v115
	v_pk_add_f32 v[60:61], v[60:61], v[178:179]
	v_pk_add_f32 v[62:63], v[62:63], v[180:181]
	v_pk_fma_f32 v[182:183], v[60:61], v[60:61], v[182:183]
	v_pk_fma_f32 v[184:185], v[62:63], v[62:63], v[184:185]
	v_pk_add_f32 v[182:183], v[182:183], v[184:185]
	s_nop 0
	v_add_f32_e32 v180, v182, v183
	ds_bpermute_b32 v178, v120, v180
	s_waitcnt lgkmcnt(0)
	v_add_f32_e32 v180, v180, v178
	ds_bpermute_b32 v178, v121, v180
	s_waitcnt lgkmcnt(0)
	v_add_f32_e32 v180, v180, v178
	ds_bpermute_b32 v178, v122, v180
	s_waitcnt lgkmcnt(0)
	v_add_f32_e32 v180, v180, v178
	ds_bpermute_b32 v178, v123, v180
	s_waitcnt lgkmcnt(0)
	v_add_f32_e32 v180, v180, v178
	ds_bpermute_b32 v178, v124, v180
	s_waitcnt lgkmcnt(0)
	v_add_f32_e32 v180, v180, v178
	ds_bpermute_b32 v178, v125, v180
	s_waitcnt lgkmcnt(0)
; __device__ __forceinline__ unsigned pk2_rne(float lo, float hi) { const f32x2_t f = {lo, hi}; return __builtin_bit_cast(unsigned, __builtin_convertvector(f, bf16x2_t)); }
; __device__ __forceinline__ float bflo(unsigned w) { return __uint_as_float(w << 16); }
; __device__ __forceinline__ float bfhi(unsigned w) { return __uint_as_float(w & 0xffff0000u); }
; __device__ __forceinline__ void rows_norm_mod(Ctx& X, const float* src, const bf16_t* delta, float* x1out, const float* w, const float* sc, const float* sh, bf16_t* dst, bool do_cs) {
;     ...
;             for (int j = 0; j < 8; ++j) { const u32x2 d2 = dr[64 * j]; v[j][0] += bflo(d2.x); v[j][1] += bfhi(d2.x); v[j][2] += bflo(d2.y); v[j][3] += bfhi(d2.y); }
;             if (x1out) {
;                 f32x4* xo = (f32x4*)(x1out + (size_t)row * D) + X.lane;
; #pragma unroll
;                 for (int j = 0; j < 8; ++j) xo[64 * j] = v[j];
;             }
;         }
; #pragma unroll
;         for (int j = 0; j < 8; ++j) ss += (v[j][0] * v[j][0] + v[j][1] * v[j][1]) + (v[j][2] * v[j][2] + v[j][3] * v[j][3]);
;         const float r = rsqrtf(wave_sum(ss) * (1.f / D) + EPS);
;         u32x2* o8 = (u32x2*)(dst + (size_t)row * D) + X.lane;
; #pragma unroll
;         for (int j = 0; j < 8; ++j) {
;             const f32x4 y = (v[j] * r) * pa[j] + pb[j];
;             u32x2 p; p.x = pk2_rne(y[0], y[1]); p.y = pk2_rne(y[2], y[3]); o8[64 * j] = p;
;         }
	v_add_f32_e32 v180, v180, v178
	v_fmamk_f32 v180, v180, 0x3a000000, v126
	v_mul_f32_e32 v178, 0x4b800000, v180
	v_cmp_gt_f32_e32 vcc, s2, v180
	s_nop 1
	v_cndmask_b32_e32 v180, v180, v178, vcc
	v_rsq_f32_e32 v180, v180
	s_nop 0
	v_mul_f32_e32 v178, 0x45800000, v180
	v_cndmask_b32_e32 v178, v180, v178, vcc
	v_pk_mul_f32 v[32:33], v[32:33], v[178:179] op_sel_hi:[1,0]
	v_pk_mul_f32 v[34:35], v[34:35], v[178:179] op_sel_hi:[1,0]
	v_pk_mul_f32 v[36:37], v[36:37], v[178:179] op_sel_hi:[1,0]
	v_pk_mul_f32 v[38:39], v[38:39], v[178:179] op_sel_hi:[1,0]
	v_pk_mul_f32 v[40:41], v[40:41], v[178:179] op_sel_hi:[1,0]
	v_pk_mul_f32 v[42:43], v[42:43], v[178:179] op_sel_hi:[1,0]
	v_pk_mul_f32 v[44:45], v[44:45], v[178:179] op_sel_hi:[1,0]
	v_pk_mul_f32 v[46:47], v[46:47], v[178:179] op_sel_hi:[1,0]
	v_pk_mul_f32 v[48:49], v[48:49], v[178:179] op_sel_hi:[1,0]
	v_pk_mul_f32 v[50:51], v[50:51], v[178:179] op_sel_hi:[1,0]
	v_pk_mul_f32 v[52:53], v[52:53], v[178:179] op_sel_hi:[1,0]
	v_pk_mul_f32 v[54:55], v[54:55], v[178:179] op_sel_hi:[1,0]
	v_pk_mul_f32 v[56:57], v[56:57], v[178:179] op_sel_hi:[1,0]
	v_pk_mul_f32 v[58:59], v[58:59], v[178:179] op_sel_hi:[1,0]
	v_pk_mul_f32 v[60:61], v[60:61], v[178:179] op_sel_hi:[1,0]
	v_pk_mul_f32 v[62:63], v[62:63], v[178:179] op_sel_hi:[1,0]
	v_pk_fma_f32 v[32:33], v[66:67], v[32:33], v[0:1]
	v_pk_fma_f32 v[34:35], v[64:65], v[34:35], v[2:3]
	v_pk_fma_f32 v[36:37], v[70:71], v[36:37], v[4:5]
	v_pk_fma_f32 v[38:39], v[68:69], v[38:39], v[6:7]
	v_pk_fma_f32 v[40:41], v[74:75], v[40:41], v[8:9]
	v_pk_fma_f32 v[42:43], v[72:73], v[42:43], v[10:11]
	v_pk_fma_f32 v[44:45], v[78:79], v[44:45], v[12:13]
	v_pk_fma_f32 v[46:47], v[76:77], v[46:47], v[14:15]
	v_pk_fma_f32 v[48:49], v[82:83], v[48:49], v[16:17]
	v_pk_fma_f32 v[50:51], v[80:81], v[50:51], v[18:19]
	v_pk_fma_f32 v[52:53], v[86:87], v[52:53], v[20:21]
	v_pk_fma_f32 v[54:55], v[84:85], v[54:55], v[22:23]
	v_pk_fma_f32 v[56:57], v[90:91], v[56:57], v[24:25]
	v_pk_fma_f32 v[58:59], v[88:89], v[58:59], v[26:27]
	v_pk_fma_f32 v[60:61], v[94:95], v[60:61], v[28:29]
	v_pk_fma_f32 v[62:63], v[92:93], v[62:63], v[30:31]
	v_cvt_pk_bf16_f32 v32, v32, v33
	v_cvt_pk_bf16_f32 v33, v34, v35
	v_cvt_pk_bf16_f32 v36, v36, v37
	v_cvt_pk_bf16_f32 v37, v38, v39
	v_cvt_pk_bf16_f32 v40, v40, v41
	v_cvt_pk_bf16_f32 v41, v42, v43
	v_cvt_pk_bf16_f32 v44, v44, v45
	v_cvt_pk_bf16_f32 v45, v46, v47
	v_cvt_pk_bf16_f32 v48, v48, v49
	v_cvt_pk_bf16_f32 v49, v50, v51
	v_cvt_pk_bf16_f32 v52, v52, v53
	v_cvt_pk_bf16_f32 v53, v54, v55
	v_cvt_pk_bf16_f32 v56, v56, v57
	v_cvt_pk_bf16_f32 v57, v58, v59
	v_cvt_pk_bf16_f32 v60, v60, v61
	v_cvt_pk_bf16_f32 v61, v62, v63
	global_store_dwordx2 v188, v[32:33], s[14:15] offset:0
	global_store_dwordx2 v188, v[36:37], s[14:15] offset:512
	global_store_dwordx2 v188, v[40:41], s[14:15] offset:1024
	global_store_dwordx2 v188, v[44:45], s[14:15] offset:1536
	global_store_dwordx2 v188, v[48:49], s[14:15] offset:2048
	global_store_dwordx2 v188, v[52:53], s[14:15] offset:2560
	global_store_dwordx2 v188, v[56:57], s[14:15] offset:3072
	global_store_dwordx2 v188, v[60:61], s[14:15] offset:3584
	s_add_u32 s14, s14, s6
	s_addc_u32 s15, s15, s7
	s_waitcnt vmcnt(8)
	v_lshlrev_b32_e32 v178, 16, v162
	v_and_b32_e32 v179, 0xffff0000, v162
	v_lshlrev_b32_e32 v180, 16, v163
	v_and_b32_e32 v181, 0xffff0000, v163
	v_pk_add_f32 v[130:131], v[130:131], v[178:179]
	v_pk_add_f32 v[132:133], v[132:133], v[180:181]
	v_pk_mul_f32 v[182:183], v[130:131], v[130:131]
	v_pk_mul_f32 v[184:185], v[132:133], v[132:133]
	v_lshlrev_b32_e32 v178, 16, v164
	v_and_b32_e32 v179, 0xffff0000, v164
	v_lshlrev_b32_e32 v180, 16, v165
	v_and_b32_e32 v181, 0xffff0000, v165
	v_pk_add_f32 v[134:135], v[134:135], v[178:179]
	v_pk_add_f32 v[136:137], v[136:137], v[180:181]
	v_pk_fma_f32 v[182:183], v[134:135], v[134:135], v[182:183]
	v_pk_fma_f32 v[184:185], v[136:137], v[136:137], v[184:185]
	v_lshlrev_b32_e32 v178, 16, v166
	v_and_b32_e32 v179, 0xffff0000, v166
	v_lshlrev_b32_e32 v180, 16, v167
	v_and_b32_e32 v181, 0xffff0000, v167
	v_pk_add_f32 v[138:139], v[138:139], v[178:179]
	v_pk_add_f32 v[140:141], v[140:141], v[180:181]
	v_pk_fma_f32 v[182:183], v[138:139], v[138:139], v[182:183]
	v_pk_fma_f32 v[184:185], v[140:141], v[140:141], v[184:185]
	v_lshlrev_b32_e32 v178, 16, v168
	v_and_b32_e32 v179, 0xffff0000, v168
	v_lshlrev_b32_e32 v180, 16, v169
	v_and_b32_e32 v181, 0xffff0000, v169
	v_pk_add_f32 v[142:143], v[142:143], v[178:179]
	v_pk_add_f32 v[144:145], v[144:145], v[180:181]
	v_pk_fma_f32 v[182:183], v[142:143], v[142:143], v[182:183]
	v_pk_fma_f32 v[184:185], v[144:145], v[144:145], v[184:185]
	v_lshlrev_b32_e32 v178, 16, v170
	v_and_b32_e32 v179, 0xffff0000, v170
	v_lshlrev_b32_e32 v180, 16, v171
	v_and_b32_e32 v181, 0xffff0000, v171
	v_pk_add_f32 v[146:147], v[146:147], v[178:179]
	v_pk_add_f32 v[148:149], v[148:149], v[180:181]
	v_pk_fma_f32 v[182:183], v[146:147], v[146:147], v[182:183]
	v_pk_fma_f32 v[184:185], v[148:149], v[148:149], v[184:185]
	v_lshlrev_b32_e32 v178, 16, v172
	v_and_b32_e32 v179, 0xffff0000, v172
	v_lshlrev_b32_e32 v180, 16, v173
	v_and_b32_e32 v181, 0xffff0000, v173
	v_pk_add_f32 v[150:151], v[150:151], v[178:179]
	v_pk_add_f32 v[152:153], v[152:153], v[180:181]
	v_pk_fma_f32 v[182:183], v[150:151], v[150:151], v[182:183]
	v_pk_fma_f32 v[184:185], v[152:153], v[152:153], v[184:185]
	v_lshlrev_b32_e32 v178, 16, v174
	v_and_b32_e32 v179, 0xffff0000, v174
	v_lshlrev_b32_e32 v180, 16, v175
	v_and_b32_e32 v181, 0xffff0000, v175
	v_pk_add_f32 v[154:155], v[154:155], v[178:179]
	v_pk_add_f32 v[156:157], v[156:157], v[180:181]
	v_pk_fma_f32 v[182:183], v[154:155], v[154:155], v[182:183]
	v_pk_fma_f32 v[184:185], v[156:157], v[156:157], v[184:185]
	v_lshlrev_b32_e32 v178, 16, v176
	v_and_b32_e32 v179, 0xffff0000, v176
	v_lshlrev_b32_e32 v180, 16, v177
	v_and_b32_e32 v181, 0xffff0000, v177
	v_pk_add_f32 v[158:159], v[158:159], v[178:179]
	v_pk_add_f32 v[160:161], v[160:161], v[180:181]
	v_pk_fma_f32 v[182:183], v[158:159], v[158:159], v[182:183]
	v_pk_fma_f32 v[184:185], v[160:161], v[160:161], v[184:185]
	v_pk_add_f32 v[182:183], v[182:183], v[184:185]
	s_nop 0
	v_add_f32_e32 v180, v182, v183
	ds_bpermute_b32 v178, v120, v180
	s_waitcnt lgkmcnt(0)
; __device__ __forceinline__ unsigned pk2_rne(float lo, float hi) { const f32x2_t f = {lo, hi}; return __builtin_bit_cast(unsigned, __builtin_convertvector(f, bf16x2_t)); }
; __device__ __forceinline__ void rows_norm_mod(Ctx& X, const float* src, const bf16_t* delta, float* x1out, const float* w, const float* sc, const float* sh, bf16_t* dst, bool do_cs) {
;     ...
;         const float r = rsqrtf(wave_sum(ss) * (1.f / D) + EPS);
;         u32x2* o8 = (u32x2*)(dst + (size_t)row * D) + X.lane;
; #pragma unroll
;         for (int j = 0; j < 8; ++j) {
;             const f32x4 y = (v[j] * r) * pa[j] + pb[j];
;             u32x2 p; p.x = pk2_rne(y[0], y[1]); p.y = pk2_rne(y[2], y[3]); o8[64 * j] = p;
;         }
	v_add_f32_e32 v180, v180, v178
	ds_bpermute_b32 v178, v121, v180
	s_waitcnt lgkmcnt(0)
	v_add_f32_e32 v180, v180, v178
	ds_bpermute_b32 v178, v122, v180
	s_waitcnt lgkmcnt(0)
	v_add_f32_e32 v180, v180, v178
	ds_bpermute_b32 v178, v123, v180
	s_waitcnt lgkmcnt(0)
	v_add_f32_e32 v180, v180, v178
	ds_bpermute_b32 v178, v124, v180
	s_waitcnt lgkmcnt(0)
	v_add_f32_e32 v180, v180, v178
	ds_bpermute_b32 v178, v125, v180
	s_waitcnt lgkmcnt(0)
	v_add_f32_e32 v180, v180, v178
	v_fmamk_f32 v180, v180, 0x3a000000, v126
	v_mul_f32_e32 v178, 0x4b800000, v180
	v_cmp_gt_f32_e32 vcc, s2, v180
	s_nop 1
	v_cndmask_b32_e32 v180, v180, v178, vcc
	v_rsq_f32_e32 v180, v180
	s_nop 0
	v_mul_f32_e32 v178, 0x45800000, v180
	v_cndmask_b32_e32 v178, v180, v178, vcc
	v_pk_mul_f32 v[130:131], v[130:131], v[178:179] op_sel_hi:[1,0]
	v_pk_mul_f32 v[132:133], v[132:133], v[178:179] op_sel_hi:[1,0]
	v_pk_mul_f32 v[134:135], v[134:135], v[178:179] op_sel_hi:[1,0]
	v_pk_mul_f32 v[136:137], v[136:137], v[178:179] op_sel_hi:[1,0]
	v_pk_mul_f32 v[138:139], v[138:139], v[178:179] op_sel_hi:[1,0]
	v_pk_mul_f32 v[140:141], v[140:141], v[178:179] op_sel_hi:[1,0]
	v_pk_mul_f32 v[142:143], v[142:143], v[178:179] op_sel_hi:[1,0]
	v_pk_mul_f32 v[144:145], v[144:145], v[178:179] op_sel_hi:[1,0]
	v_pk_mul_f32 v[146:147], v[146:147], v[178:179] op_sel_hi:[1,0]
	v_pk_mul_f32 v[148:149], v[148:149], v[178:179] op_sel_hi:[1,0]
	v_pk_mul_f32 v[150:151], v[150:151], v[178:179] op_sel_hi:[1,0]
	v_pk_mul_f32 v[152:153], v[152:153], v[178:179] op_sel_hi:[1,0]
	v_pk_mul_f32 v[154:155], v[154:155], v[178:179] op_sel_hi:[1,0]
	v_pk_mul_f32 v[156:157], v[156:157], v[178:179] op_sel_hi:[1,0]
	v_pk_mul_f32 v[158:159], v[158:159], v[178:179] op_sel_hi:[1,0]
	v_pk_mul_f32 v[160:161], v[160:161], v[178:179] op_sel_hi:[1,0]
	v_pk_fma_f32 v[130:131], v[66:67], v[130:131], v[0:1]
	v_pk_fma_f32 v[132:133], v[64:65], v[132:133], v[2:3]
	v_pk_fma_f32 v[134:135], v[70:71], v[134:135], v[4:5]
	v_pk_fma_f32 v[136:137], v[68:69], v[136:137], v[6:7]
	v_pk_fma_f32 v[138:139], v[74:75], v[138:139], v[8:9]
	v_pk_fma_f32 v[140:141], v[72:73], v[140:141], v[10:11]
	v_pk_fma_f32 v[142:143], v[78:79], v[142:143], v[12:13]
	v_pk_fma_f32 v[144:145], v[76:77], v[144:145], v[14:15]
	v_pk_fma_f32 v[146:147], v[82:83], v[146:147], v[16:17]
	v_pk_fma_f32 v[148:149], v[80:81], v[148:149], v[18:19]
	v_pk_fma_f32 v[150:151], v[86:87], v[150:151], v[20:21]
	v_pk_fma_f32 v[152:153], v[84:85], v[152:153], v[22:23]
	v_pk_fma_f32 v[154:155], v[90:91], v[154:155], v[24:25]
	v_pk_fma_f32 v[156:157], v[88:89], v[156:157], v[26:27]
	v_pk_fma_f32 v[158:159], v[94:95], v[158:159], v[28:29]
	v_pk_fma_f32 v[160:161], v[92:93], v[160:161], v[30:31]
	v_cvt_pk_bf16_f32 v130, v130, v131
	v_cvt_pk_bf16_f32 v131, v132, v133
	v_cvt_pk_bf16_f32 v134, v134, v135
	v_cvt_pk_bf16_f32 v135, v136, v137
	v_cvt_pk_bf16_f32 v138, v138, v139
	v_cvt_pk_bf16_f32 v139, v140, v141
	v_cvt_pk_bf16_f32 v142, v142, v143
	v_cvt_pk_bf16_f32 v143, v144, v145
	v_cvt_pk_bf16_f32 v146, v146, v147
	v_cvt_pk_bf16_f32 v147, v148, v149
	v_cvt_pk_bf16_f32 v150, v150, v151
	v_cvt_pk_bf16_f32 v151, v152, v153
	v_cvt_pk_bf16_f32 v154, v154, v155
	v_cvt_pk_bf16_f32 v155, v156, v157
	v_cvt_pk_bf16_f32 v158, v158, v159
	v_cvt_pk_bf16_f32 v159, v160, v161
	global_store_dwordx2 v188, v[130:131], s[14:15] offset:0
	global_store_dwordx2 v188, v[134:135], s[14:15] offset:512
	global_store_dwordx2 v188, v[138:139], s[14:15] offset:1024
	global_store_dwordx2 v188, v[142:143], s[14:15] offset:1536
	global_store_dwordx2 v188, v[146:147], s[14:15] offset:2048
	global_store_dwordx2 v188, v[150:151], s[14:15] offset:2560
	global_store_dwordx2 v188, v[154:155], s[14:15] offset:3072
	global_store_dwordx2 v188, v[158:159], s[14:15] offset:3584
	s_add_u32 s14, s14, s6
	s_addc_u32 s15, s15, s7
	s_branch .LBB0_868
